# rs loads issued at tile top (before K loop) into v240-247; epilogue of EP_IN/EP_UP has no vmcnt wait
# speedup vs baseline: 1.0099x; 1.0031x over previous
;   DI bool next(int i, Unit& u) const {
;     const long L = (long)i * G + c; if (L >= nwg) return false;
;     int wgid = (int)L; { const int q = nwg / NXCD, r = nwg % NXCD, xcd = wgid % NXCD, off = wgid / NXCD; wgid = (xcd < r ? xcd * (q + 1) : r * (q + 1) + (xcd - r) * q) + off; }
;     const int nig = wgm * nN, gid = wgid / nig, fm = gid * wgm, gsz = (nM - fm) < wgm ? (nM - fm) : wgm;
;     u.pm = fm + ((wgid % nig) % gsz); u.pn = (wgid % nig) / gsz; return true;
;   }
;   DI void operator()(const f32x4 (&acc)[2][2][4][2], const pg8::Unit& u, int wr, int wc, int fr, int fq) const {
;     ...
;         const int row = u.pm * 256 + ai * 128 + wr * 64 + m * 16 + fr;
;         const int grow = rowbase + row;
;         float rs = 1.f;
;         if (MODE == EP_IN) rs = ((const float*)(ws + OFF_RS0))[grow];
;         if (MODE == EP_UP) rs = ((const float*)(ws + OFF_RS2))[grow];
.LBB0_181:
	v_lshl_add_u32 v248, s4, 8, v164
	v_ashrrev_i32_e32 v249, 31, v248
	v_lshl_add_u64 v[248:249], v[248:249], 2, s[12:13]
	global_load_dword v247, v[248:249], off
	global_load_dword v240, v[248:249], off offset:64
	global_load_dword v241, v[248:249], off offset:128
	global_load_dword v242, v[248:249], off offset:192
	global_load_dword v243, v[248:249], off offset:512
	global_load_dword v244, v[248:249], off offset:576
	global_load_dword v245, v[248:249], off offset:640
	global_load_dword v246, v[248:249], off offset:704
	s_add_i32 s58, s58, 1
	s_mul_i32 s2, s58, s52
	s_mul_hi_u32 s3, s58, s68
	s_add_i32 s3, s3, s2
	s_mul_i32 s2, s58, s68
	s_add_u32 s26, s2, s60
	s_addc_u32 s27, s3, s53
	v_cmp_gt_i64_e64 s[2:3], s[26:27], v[148:149]
	s_and_b64 vcc, exec, s[2:3]
	s_cbranch_vccnz .LBB0_183
	s_ashr_i32 s5, s26, 31
	s_lshr_b32 s5, s5, 29
	s_add_i32 s5, s26, s5
	s_ashr_i32 s8, s5, 3
	s_and_b32 s5, s5, -8
	s_sub_i32 s5, s26, s5
	s_cmp_lt_i32 s5, 0
	s_cselect_b32 s22, s54, 0x110
	s_mul_i32 s5, s22, s5
	s_add_i32 s5, s5, s8
	s_mul_hi_i32 s8, s5, 0x78787879
	s_lshr_b32 s22, s8, 31
	s_ashr_i32 s8, s8, 6
	s_add_i32 s8, s8, s22
	s_lshl_b32 s23, s8, 3
	s_sub_i32 s22, 0x80, s23
	s_min_i32 s24, s22, 8
	s_abs_i32 s22, s24
	v_cvt_f32_u32_e32 v2, s22
	s_sub_i32 s28, 0, s22
	s_mulk_i32 s8, 0x88
	s_sub_i32 s5, s5, s8
	v_rcp_iflag_f32_e32 v2, v2
	s_abs_i32 s8, s5
	s_xor_b32 s25, s5, s24
	s_ashr_i32 s25, s25, 31
	v_mul_f32_e32 v2, 0x4f7ffffe, v2
	v_cvt_u32_f32_e32 v2, v2
	s_nop 0
	v_readfirstlane_b32 s29, v2
	s_mul_i32 s28, s28, s29
	s_mul_hi_u32 s28, s29, s28
	s_add_i32 s29, s29, s28
	s_mul_hi_u32 s28, s8, s29
	s_mul_i32 s29, s28, s22
	s_sub_i32 s8, s8, s29
	s_add_i32 s34, s28, 1
	s_sub_i32 s29, s8, s22
	s_cmp_ge_u32 s8, s22
	s_cselect_b32 s28, s34, s28
	s_cselect_b32 s8, s29, s8
	s_add_i32 s29, s28, 1
	s_cmp_ge_u32 s8, s22
	s_cselect_b32 s8, s29, s28
	s_xor_b32 s8, s8, s25
	s_sub_i32 s22, s8, s25
	s_mul_i32 s8, s22, s24
	s_sub_i32 s5, s5, s8
	s_add_i32 s24, s5, s23

; #define PG8_STAGE(bufoff, gbase, voff) do { _Pragma("unroll") for (int _i = 0; _i < 2; ++_i) \
;     __builtin_amdgcn_global_load_lds((const unsigned*)((const char*)(gbase) + (voff)[_i]), (LAS unsigned*)(lds + (bufoff) + ldsw + _i * 8192), 16, 0, 0); } while (0)
; #define PG8_LDA(dst, b, h) do { _Pragma("unroll") for (int m = 0; m < 4; ++m) _Pragma("unroll") for (int k = 0; k < 2; ++k) dst[m][k] = *(const LAS bf16x8*)(lds + PG8_SA(b, h) + aoff + m * 2048 + k * 1024); } while (0)
; #define PG8_LDB(dst, b, h) do { _Pragma("unroll") for (int n = 0; n < 2; ++n) _Pragma("unroll") for (int k = 0; k < 2; ++k) dst[n][k] = *(const LAS bf16x8*)(lds + PG8_SB(b, h) + boff + n * 2048 + k * 1024); } while (0)
; #define PG8_MMA(ai, bj, At, Bt) do { __builtin_amdgcn_s_setprio(1); _Pragma("unroll") for (int m = 0; m < 4; ++m) _Pragma("unroll") for (int n = 0; n < 2; ++n) _Pragma("unroll") for (int k = 0; k < 2; ++k) \
;     acc[ai][bj][m][n] = __builtin_amdgcn_mfma_f32_16x16x32_bf16(Bt[n][k], At[m][k], acc[ai][bj][m][n], 0, 0, 0); __builtin_amdgcn_s_setprio(0); } while (0)
; #define PG8_WAIT_L(n) asm volatile("s_waitcnt lgkmcnt(" #n ")" ::: "memory")
; #define PG8_BAR __builtin_amdgcn_s_barrier()
; #define PG8_SCHED __builtin_amdgcn_sched_barrier(0)
; template <class Epi>
; DI void gemm_phase(LAS unsigned char* lds, const Gemm g, const StaticOrder& S, const Epi& E) {
;     ...
;       PG8_LDB(B0, 0, 0); PG8_SCHED; PG8_LDA(At, 0, 0); PG8_STAGE(PG8_SA(1, 1), a1 + hstepA, voffA);
;       PG8_WAIT_L(8); PG8_BAR; PG8_WAIT_L(0); PG8_MMA(0, 0, At, B0); PG8_BAR; PG8_SCHED;
;       PG8_LDB(B1, 0, 1); PG8_STAGE(PG8_SB(0, 0), b2, voffB);
;       PG8_BAR; PG8_WAIT_L(0); PG8_MMA(0, 1, At, B1); PG8_BAR;
;       PG8_LDA(At, 0, 1); PG8_STAGE(PG8_SA(0, 0), a2, voffA);
;       PG8_BAR; PG8_WAIT_L(0); PG8_MMA(1, 0, At, B0); PG8_BAR; PG8_SCHED;
.LBB0_184:
	ds_read_b128 v[150:153], v166
	ds_read_b128 v[154:157], v166 offset:1024
	ds_read_b128 v[158:161], v166 offset:2048
	ds_read_b128 v[170:173], v166 offset:3072
	s_add_u32 s30, s6, 0xfff80080
	s_addc_u32 s31, s7, -1
	s_cmp_eq_u32 s39, 28
	s_cselect_b32 s35, s5, s31
	s_cselect_b32 s34, s8, s30
	s_cselect_b32 s31, s23, s38
	s_cselect_b32 s30, s25, s37
	v_lshl_add_u64 v[162:163], s[6:7], 0, v[142:143]
	s_add_i32 m0, s45, 0xc000
	ds_read_b128 v[174:177], v167
	ds_read_b128 v[178:181], v167 offset:1024
	ds_read_b128 v[182:185], v167 offset:2048
	ds_read_b128 v[186:189], v167 offset:3072
	ds_read_b128 v[190:193], v167 offset:4096
	ds_read_b128 v[194:197], v167 offset:5120
	ds_read_b128 v[198:201], v167 offset:6144
	ds_read_b128 v[202:205], v167 offset:7168
	global_load_lds_dwordx4 v[162:163], off
	v_lshl_add_u64 v[162:163], s[6:7], 0, v[144:145]
	s_add_i32 m0, s45, 0xe000
	s_nop 0
	global_load_lds_dwordx4 v[162:163], off
	s_waitcnt lgkmcnt(8)
	s_barrier
	s_waitcnt lgkmcnt(0)
	s_setprio 1
	s_waitcnt lgkmcnt(0)
	v_mfma_f32_16x16x32_bf16 v[126:129], v[150:153], v[174:177], v[126:129]
	v_mfma_f32_16x16x32_bf16 v[122:125], v[158:161], v[174:177], v[122:125]
	v_mfma_f32_16x16x32_bf16 v[110:113], v[150:153], v[182:185], v[110:113]
	v_mfma_f32_16x16x32_bf16 v[106:109], v[158:161], v[182:185], v[106:109]
	v_mfma_f32_16x16x32_bf16 v[94:97], v[150:153], v[190:193], v[94:97]
	v_mfma_f32_16x16x32_bf16 v[90:93], v[158:161], v[190:193], v[90:93]
	v_mfma_f32_16x16x32_bf16 v[78:81], v[150:153], v[198:201], v[78:81]
	v_mfma_f32_16x16x32_bf16 v[74:77], v[158:161], v[198:201], v[74:77]
	v_mfma_f32_16x16x32_bf16 v[126:129], v[154:157], v[178:181], v[126:129]
	v_mfma_f32_16x16x32_bf16 v[122:125], v[170:173], v[178:181], v[122:125]
	v_mfma_f32_16x16x32_bf16 v[110:113], v[154:157], v[186:189], v[110:113]
	v_mfma_f32_16x16x32_bf16 v[106:109], v[170:173], v[186:189], v[106:109]
	v_mfma_f32_16x16x32_bf16 v[94:97], v[154:157], v[194:197], v[94:97]
	v_mfma_f32_16x16x32_bf16 v[90:93], v[170:173], v[194:197], v[90:93]
	v_mfma_f32_16x16x32_bf16 v[78:81], v[154:157], v[202:205], v[78:81]
	v_mfma_f32_16x16x32_bf16 v[74:77], v[170:173], v[202:205], v[74:77]
	s_setprio 0
	s_barrier
	s_add_i32 s40, s55, s44
	v_lshl_add_u64 v[162:163], s[30:31], 0, v[132:133]
	s_mov_b32 m0, s40
	ds_read_b128 v[206:209], v168
	ds_read_b128 v[210:213], v168 offset:1024
	ds_read_b128 v[214:217], v168 offset:2048
	ds_read_b128 v[218:221], v168 offset:3072
	global_load_lds_dwordx4 v[162:163], off
	v_lshl_add_u64 v[222:223], s[30:31], 0, v[136:137]
	s_add_i32 m0, s40, 0x2000
	s_nop 0
	global_load_lds_dwordx4 v[222:223], off
	s_barrier
	s_waitcnt lgkmcnt(0)
	s_setprio 1
	s_waitcnt lgkmcnt(0)
	v_mfma_f32_16x16x32_bf16 v[118:121], v[206:209], v[174:177], v[118:121]
	v_mfma_f32_16x16x32_bf16 v[114:117], v[214:217], v[174:177], v[114:117]
	v_mfma_f32_16x16x32_bf16 v[102:105], v[206:209], v[182:185], v[102:105]
	v_mfma_f32_16x16x32_bf16 v[98:101], v[214:217], v[182:185], v[98:101]
	v_mfma_f32_16x16x32_bf16 v[86:89], v[206:209], v[190:193], v[86:89]
	v_mfma_f32_16x16x32_bf16 v[82:85], v[214:217], v[190:193], v[82:85]
	v_mfma_f32_16x16x32_bf16 v[70:73], v[206:209], v[198:201], v[70:73]
	v_mfma_f32_16x16x32_bf16 v[66:69], v[214:217], v[198:201], v[66:69]
	v_mfma_f32_16x16x32_bf16 v[118:121], v[210:213], v[178:181], v[118:121]
	v_mfma_f32_16x16x32_bf16 v[114:117], v[218:221], v[178:181], v[114:117]
	v_mfma_f32_16x16x32_bf16 v[102:105], v[210:213], v[186:189], v[102:105]
	v_mfma_f32_16x16x32_bf16 v[98:101], v[218:221], v[186:189], v[98:101]
	v_mfma_f32_16x16x32_bf16 v[86:89], v[210:213], v[194:197], v[86:89]
	v_mfma_f32_16x16x32_bf16 v[82:85], v[218:221], v[194:197], v[82:85]
	v_mfma_f32_16x16x32_bf16 v[70:73], v[210:213], v[202:205], v[70:73]
	v_mfma_f32_16x16x32_bf16 v[66:69], v[218:221], v[202:205], v[66:69]
	s_setprio 0
	s_mov_b32 m0, s45
	v_lshl_add_u64 v[224:225], s[34:35], 0, v[130:131]
	s_barrier
	ds_read_b128 v[174:177], v167 offset:16384
	ds_read_b128 v[178:181], v167 offset:17408
	ds_read_b128 v[182:185], v167 offset:18432
	ds_read_b128 v[186:189], v167 offset:19456
	ds_read_b128 v[190:193], v167 offset:20480
	ds_read_b128 v[194:197], v167 offset:21504
	ds_read_b128 v[198:201], v167 offset:22528
	ds_read_b128 v[202:205], v167 offset:23552
	global_load_lds_dwordx4 v[224:225], off
	v_lshl_add_u64 v[226:227], s[34:35], 0, v[134:135]
	s_mov_b32 m0, s46
	s_nop 0
	global_load_lds_dwordx4 v[226:227], off
	s_barrier
	s_waitcnt lgkmcnt(0)
	s_setprio 1
	s_waitcnt lgkmcnt(0)
	v_mfma_f32_16x16x32_bf16 v[62:65], v[150:153], v[174:177], v[62:65]
	v_mfma_f32_16x16x32_bf16 v[58:61], v[158:161], v[174:177], v[58:61]
	v_mfma_f32_16x16x32_bf16 v[46:49], v[150:153], v[182:185], v[46:49]
	v_mfma_f32_16x16x32_bf16 v[42:45], v[158:161], v[182:185], v[42:45]
	v_mfma_f32_16x16x32_bf16 v[30:33], v[150:153], v[190:193], v[30:33]
	v_mfma_f32_16x16x32_bf16 v[26:29], v[158:161], v[190:193], v[26:29]
	v_mfma_f32_16x16x32_bf16 v[14:17], v[150:153], v[198:201], v[14:17]
	v_mfma_f32_16x16x32_bf16 v[10:13], v[158:161], v[198:201], v[10:13]
	v_mfma_f32_16x16x32_bf16 v[62:65], v[154:157], v[178:181], v[62:65]
	v_mfma_f32_16x16x32_bf16 v[58:61], v[170:173], v[178:181], v[58:61]
	v_mfma_f32_16x16x32_bf16 v[46:49], v[154:157], v[186:189], v[46:49]
	v_mfma_f32_16x16x32_bf16 v[42:45], v[170:173], v[186:189], v[42:45]
	v_mfma_f32_16x16x32_bf16 v[30:33], v[154:157], v[194:197], v[30:33]
	v_mfma_f32_16x16x32_bf16 v[26:29], v[170:173], v[194:197], v[26:29]
	v_mfma_f32_16x16x32_bf16 v[14:17], v[154:157], v[202:205], v[14:17]
	v_mfma_f32_16x16x32_bf16 v[10:13], v[170:173], v[202:205], v[10:13]
	s_setprio 0
	s_barrier
; #define PG8_STAGE(bufoff, gbase, voff) do { _Pragma("unroll") for (int _i = 0; _i < 2; ++_i) \
;     __builtin_amdgcn_global_load_lds((const unsigned*)((const char*)(gbase) + (voff)[_i]), (LAS unsigned*)(lds + (bufoff) + ldsw + _i * 8192), 16, 0, 0); } while (0)
; #define PG8_LDA(dst, b, h) do { _Pragma("unroll") for (int m = 0; m < 4; ++m) _Pragma("unroll") for (int k = 0; k < 2; ++k) dst[m][k] = *(const LAS bf16x8*)(lds + PG8_SA(b, h) + aoff + m * 2048 + k * 1024); } while (0)
; #define PG8_LDB(dst, b, h) do { _Pragma("unroll") for (int n = 0; n < 2; ++n) _Pragma("unroll") for (int k = 0; k < 2; ++k) dst[n][k] = *(const LAS bf16x8*)(lds + PG8_SB(b, h) + boff + n * 2048 + k * 1024); } while (0)
; #define PG8_MMA(ai, bj, At, Bt) do { __builtin_amdgcn_s_setprio(1); _Pragma("unroll") for (int m = 0; m < 4; ++m) _Pragma("unroll") for (int n = 0; n < 2; ++n) _Pragma("unroll") for (int k = 0; k < 2; ++k) \
;     acc[ai][bj][m][n] = __builtin_amdgcn_mfma_f32_16x16x32_bf16(Bt[n][k], At[m][k], acc[ai][bj][m][n], 0, 0, 0); __builtin_amdgcn_s_setprio(0); } while (0)
; #define PG8_WAIT_V(n) asm volatile("s_waitcnt vmcnt(" #n ")" ::: "memory")
; #define PG8_WAIT_L(n) asm volatile("s_waitcnt lgkmcnt(" #n ")" ::: "memory")
; #define PG8_BAR __builtin_amdgcn_s_barrier()
; #define PG8_SCHED __builtin_amdgcn_sched_barrier(0)
; template <class Epi>
; DI void gemm_phase(LAS unsigned char* lds, const Gemm g, const StaticOrder& S, const Epi& E) {
;     ...
;       PG8_STAGE(PG8_SB(0, 1), b2 + hstepB, voffB);
;       PG8_WAIT_V(6); PG8_BAR; PG8_MMA(1, 1, At, B1); PG8_BAR;
;       PG8_LDB(B0, 1, 0); PG8_SCHED; PG8_LDA(At, 1, 0); PG8_STAGE(PG8_SA(0, 1), a2 + hstepA, voffA);
;       PG8_WAIT_L(8); PG8_BAR; PG8_WAIT_L(0); PG8_MMA(0, 0, At, B0); PG8_BAR; PG8_SCHED;
;       PG8_LDB(B1, 1, 1); PG8_STAGE(PG8_SB(1, 0), b3, voffB);
;       PG8_BAR; PG8_WAIT_L(0); PG8_MMA(0, 1, At, B1); PG8_BAR;
;       PG8_LDA(At, 1, 1); PG8_STAGE(PG8_SA(1, 0), a3, voffA);
	s_add_u32 s40, s30, 0x80000
	s_addc_u32 s41, s31, 0
	s_add_i32 s59, s56, s44
	v_lshl_add_u64 v[150:151], s[40:41], 0, v[132:133]
	s_mov_b32 m0, s59
	s_nop 0
	global_load_lds_dwordx4 v[150:151], off
	v_lshl_add_u64 v[150:151], s[40:41], 0, v[136:137]
	s_add_i32 m0, s59, 0x2000
	s_nop 0
	global_load_lds_dwordx4 v[150:151], off
	s_waitcnt vmcnt(6)
	s_barrier
	s_setprio 1
	v_mfma_f32_16x16x32_bf16 v[54:57], v[206:209], v[174:177], v[54:57]
	v_mfma_f32_16x16x32_bf16 v[50:53], v[214:217], v[174:177], v[50:53]
	v_mfma_f32_16x16x32_bf16 v[38:41], v[206:209], v[182:185], v[38:41]
	v_mfma_f32_16x16x32_bf16 v[34:37], v[214:217], v[182:185], v[34:37]
	v_mfma_f32_16x16x32_bf16 v[22:25], v[206:209], v[190:193], v[22:25]
	v_mfma_f32_16x16x32_bf16 v[18:21], v[214:217], v[190:193], v[18:21]
	v_mfma_f32_16x16x32_bf16 v[6:9], v[206:209], v[198:201], v[6:9]
	v_mfma_f32_16x16x32_bf16 v[2:5], v[214:217], v[198:201], v[2:5]
	v_mfma_f32_16x16x32_bf16 v[54:57], v[210:213], v[178:181], v[54:57]
	v_mfma_f32_16x16x32_bf16 v[50:53], v[218:221], v[178:181], v[50:53]
	v_mfma_f32_16x16x32_bf16 v[38:41], v[210:213], v[186:189], v[38:41]
	v_mfma_f32_16x16x32_bf16 v[34:37], v[218:221], v[186:189], v[34:37]
	v_mfma_f32_16x16x32_bf16 v[22:25], v[210:213], v[194:197], v[22:25]
	v_mfma_f32_16x16x32_bf16 v[18:21], v[218:221], v[194:197], v[18:21]
	v_mfma_f32_16x16x32_bf16 v[6:9], v[210:213], v[202:205], v[6:9]
	v_mfma_f32_16x16x32_bf16 v[2:5], v[218:221], v[202:205], v[2:5]
	s_setprio 0
	s_add_i32 s40, 0, 0x18000
	v_add_u32_e32 v138, s40, v165
	s_barrier
	ds_read_b128 v[150:153], v138
	ds_read_b128 v[154:157], v138 offset:1024
	ds_read_b128 v[158:161], v138 offset:2048
	ds_read_b128 v[170:173], v138 offset:3072
	s_add_u32 s34, s34, 0x80000
	s_addc_u32 s35, s35, 0
	s_mov_b32 m0, s47
	v_lshl_add_u64 v[206:207], s[34:35], 0, v[130:131]
	ds_read_b128 v[174:177], v167 offset:32768
	ds_read_b128 v[178:181], v167 offset:33792
	ds_read_b128 v[182:185], v167 offset:34816
	ds_read_b128 v[186:189], v167 offset:35840
	ds_read_b128 v[190:193], v167 offset:36864
	ds_read_b128 v[194:197], v167 offset:37888
	ds_read_b128 v[198:201], v167 offset:38912
	ds_read_b128 v[202:205], v167 offset:39936
	global_load_lds_dwordx4 v[206:207], off
	v_lshl_add_u64 v[206:207], s[34:35], 0, v[134:135]
	s_mov_b32 m0, s48
	s_nop 0
	global_load_lds_dwordx4 v[206:207], off
	s_waitcnt lgkmcnt(8)
	s_barrier
	s_waitcnt lgkmcnt(0)
	s_setprio 1
	s_waitcnt lgkmcnt(0)
	v_mfma_f32_16x16x32_bf16 v[126:129], v[150:153], v[174:177], v[126:129]
	v_mfma_f32_16x16x32_bf16 v[122:125], v[158:161], v[174:177], v[122:125]
	v_mfma_f32_16x16x32_bf16 v[110:113], v[150:153], v[182:185], v[110:113]
	v_mfma_f32_16x16x32_bf16 v[106:109], v[158:161], v[182:185], v[106:109]
	v_mfma_f32_16x16x32_bf16 v[94:97], v[150:153], v[190:193], v[94:97]
	v_mfma_f32_16x16x32_bf16 v[90:93], v[158:161], v[190:193], v[90:93]
	v_mfma_f32_16x16x32_bf16 v[78:81], v[150:153], v[198:201], v[78:81]
	v_mfma_f32_16x16x32_bf16 v[74:77], v[158:161], v[198:201], v[74:77]
	v_mfma_f32_16x16x32_bf16 v[126:129], v[154:157], v[178:181], v[126:129]
	v_mfma_f32_16x16x32_bf16 v[122:125], v[170:173], v[178:181], v[122:125]
	v_mfma_f32_16x16x32_bf16 v[110:113], v[154:157], v[186:189], v[110:113]
	v_mfma_f32_16x16x32_bf16 v[106:109], v[170:173], v[186:189], v[106:109]
	v_mfma_f32_16x16x32_bf16 v[94:97], v[154:157], v[194:197], v[94:97]
	v_mfma_f32_16x16x32_bf16 v[90:93], v[170:173], v[194:197], v[90:93]
	v_mfma_f32_16x16x32_bf16 v[78:81], v[154:157], v[202:205], v[78:81]
	v_mfma_f32_16x16x32_bf16 v[74:77], v[170:173], v[202:205], v[74:77]
	s_setprio 0
	s_barrier
	s_add_i32 s34, 0, 0x1c000
	s_add_i32 s35, s40, s44
	v_add_u32_e32 v138, s34, v165
	v_lshl_add_u64 v[162:163], v[162:163], 0, s[10:11]
	s_mov_b32 m0, s35
	ds_read_b128 v[206:209], v138
	ds_read_b128 v[210:213], v138 offset:1024
	ds_read_b128 v[214:217], v138 offset:2048
	ds_read_b128 v[218:221], v138 offset:3072
	global_load_lds_dwordx4 v[162:163], off
	v_lshl_add_u64 v[162:163], v[222:223], 0, s[10:11]
	s_add_i32 m0, s35, 0x2000
	s_nop 0
	global_load_lds_dwordx4 v[162:163], off
	s_barrier
; #define PG8_LDA(dst, b, h) do { _Pragma("unroll") for (int m = 0; m < 4; ++m) _Pragma("unroll") for (int k = 0; k < 2; ++k) dst[m][k] = *(const LAS bf16x8*)(lds + PG8_SA(b, h) + aoff + m * 2048 + k * 1024); } while (0)
; template <class Epi>
; DI void gemm_phase(LAS unsigned char* lds, const Gemm g, const StaticOrder& S, const Epi& E) {
;     ...
;       PG8_LDA(At, 1, 1); PG8_STAGE(PG8_SA(1, 0), a3, voffA);
;       PG8_BAR; PG8_WAIT_L(0); PG8_MMA(1, 0, At, B0); PG8_BAR; PG8_SCHED;
;       PG8_STAGE(PG8_SB(1, 1), b3 + hstepB, voffB);
;       PG8_WAIT_V(6); PG8_BAR; PG8_MMA(1, 1, At, B1); PG8_BAR;
;     }
;     E(acc, cur, wr, wc, fr, fq);
;   DI void operator()(const f32x4 (&acc)[2][2][4][2], const pg8::Unit& u, int wr, int wc, int fr, int fq) const {
;     ...
;         const int row = u.pm * 256 + ai * 128 + wr * 64 + m * 16 + fr;
;         const int grow = rowbase + row;
;         float rs = 1.f;
;         if (MODE == EP_IN) rs = ((const float*)(ws + OFF_RS0))[grow];
;         if (MODE == EP_UP) rs = ((const float*)(ws + OFF_RS2))[grow];
;         if (MODE == EP_Q || MODE == EP_KV) {
;           const f32x4* sp = (const f32x4*)(ws + OFF_SSQA) + (size_t)grow * 4 + (MODE == EP_KV ? 2 : 0);
;           const f32x4 s0 = sp[0], s1 = sp[1];
;           const float ss = (s0[0] + s0[1]) + (s0[2] + s0[3]) + (s1[0] + s1[1]) + (s1[2] + s1[3]);
;           rs = __builtin_amdgcn_rsqf(ss * (1.0f / 512) + EPS);
;           if (MODE == EP_Q) rs *= QSCALE;
;         }
;         float ssq = 0.f;
; #pragma unroll
;         for (int bj = 0; bj < 2; ++bj) {
;           f32x4 v0 = acc[ai][bj][m][0] * rs, v1 = acc[ai][bj][m][1] * rs;
;           if (MODE == EP_IN || MODE == EP_MIX || MODE == EP_DOWN) {
; #pragma unroll
;             for (int j = 0; j < 4; ++j) ssq += v0[j] * v0[j] + v1[j] * v1[j];
;           }
;           if (MODE == EP_UP) {
; #pragma unroll
;             for (int j = 0; j < 4; ++j) { float a = fmaxf(v0[j], 0.f), b = fmaxf(v1[j], 0.f); v0[j] = a * a; v1[j] = b * b; }
;           }
;           bf16_t* dst;
;           const int ct = bj * 128 + cl;
;           if (MODE == EP_IN) {
;             if (pn < 4) dst = (bf16_t*)(ws + OFF_PROJA) + (size_t)grow * 1024 + pn * 256 + ct;
;             else if (pn < 16) dst = (bf16_t*)(ws + OFF_PROJG) + (size_t)grow * 3072 + (pn - 4) * 256 + ct;
;             else dst = (bf16_t*)(ws + OFF_PROJS) + (size_t)grow * 256 + ct;
	s_waitcnt lgkmcnt(0)
	s_setprio 1
	s_waitcnt lgkmcnt(0)
	v_mfma_f32_16x16x32_bf16 v[118:121], v[206:209], v[174:177], v[118:121]
	v_mfma_f32_16x16x32_bf16 v[114:117], v[214:217], v[174:177], v[114:117]
	v_mfma_f32_16x16x32_bf16 v[102:105], v[206:209], v[182:185], v[102:105]
	v_mfma_f32_16x16x32_bf16 v[98:101], v[214:217], v[182:185], v[98:101]
	v_mfma_f32_16x16x32_bf16 v[86:89], v[206:209], v[190:193], v[86:89]
	v_mfma_f32_16x16x32_bf16 v[82:85], v[214:217], v[190:193], v[82:85]
	v_mfma_f32_16x16x32_bf16 v[70:73], v[206:209], v[198:201], v[70:73]
	v_mfma_f32_16x16x32_bf16 v[66:69], v[214:217], v[198:201], v[66:69]
	v_mfma_f32_16x16x32_bf16 v[118:121], v[210:213], v[178:181], v[118:121]
	v_mfma_f32_16x16x32_bf16 v[114:117], v[218:221], v[178:181], v[114:117]
	v_mfma_f32_16x16x32_bf16 v[102:105], v[210:213], v[186:189], v[102:105]
	v_mfma_f32_16x16x32_bf16 v[98:101], v[218:221], v[186:189], v[98:101]
	v_mfma_f32_16x16x32_bf16 v[86:89], v[210:213], v[194:197], v[86:89]
	v_mfma_f32_16x16x32_bf16 v[82:85], v[218:221], v[194:197], v[82:85]
	v_mfma_f32_16x16x32_bf16 v[70:73], v[210:213], v[202:205], v[70:73]
	v_mfma_f32_16x16x32_bf16 v[66:69], v[218:221], v[202:205], v[66:69]
	s_setprio 0
	s_mov_b32 m0, s50
	v_lshl_add_u64 v[162:163], v[224:225], 0, s[10:11]
	s_barrier
	ds_read_b128 v[174:177], v167 offset:49152
	ds_read_b128 v[178:181], v167 offset:50176
	ds_read_b128 v[182:185], v167 offset:51200
	ds_read_b128 v[186:189], v167 offset:52224
	ds_read_b128 v[190:193], v167 offset:53248
	ds_read_b128 v[194:197], v167 offset:54272
	ds_read_b128 v[198:201], v167 offset:55296
	ds_read_b128 v[202:205], v167 offset:56320
	global_load_lds_dwordx4 v[162:163], off
	v_lshl_add_u64 v[162:163], v[226:227], 0, s[10:11]
	s_mov_b32 m0, s51
	s_nop 0
	global_load_lds_dwordx4 v[162:163], off
	s_barrier
	s_waitcnt lgkmcnt(0)
	s_setprio 1
	s_waitcnt lgkmcnt(0)
	v_mfma_f32_16x16x32_bf16 v[62:65], v[150:153], v[174:177], v[62:65]
	v_mfma_f32_16x16x32_bf16 v[58:61], v[158:161], v[174:177], v[58:61]
	v_mfma_f32_16x16x32_bf16 v[46:49], v[150:153], v[182:185], v[46:49]
	v_mfma_f32_16x16x32_bf16 v[42:45], v[158:161], v[182:185], v[42:45]
	v_mfma_f32_16x16x32_bf16 v[30:33], v[150:153], v[190:193], v[30:33]
	v_mfma_f32_16x16x32_bf16 v[26:29], v[158:161], v[190:193], v[26:29]
	v_mfma_f32_16x16x32_bf16 v[14:17], v[150:153], v[198:201], v[14:17]
	v_mfma_f32_16x16x32_bf16 v[10:13], v[158:161], v[198:201], v[10:13]
	v_mfma_f32_16x16x32_bf16 v[62:65], v[154:157], v[178:181], v[62:65]
	v_mfma_f32_16x16x32_bf16 v[58:61], v[170:173], v[178:181], v[58:61]
	v_mfma_f32_16x16x32_bf16 v[46:49], v[154:157], v[186:189], v[46:49]
	v_mfma_f32_16x16x32_bf16 v[42:45], v[170:173], v[186:189], v[42:45]
	v_mfma_f32_16x16x32_bf16 v[30:33], v[154:157], v[194:197], v[30:33]
	v_mfma_f32_16x16x32_bf16 v[26:29], v[170:173], v[194:197], v[26:29]
	v_mfma_f32_16x16x32_bf16 v[14:17], v[154:157], v[202:205], v[14:17]
	v_mfma_f32_16x16x32_bf16 v[10:13], v[170:173], v[202:205], v[10:13]
	s_setprio 0
	s_barrier
	s_add_u32 s30, s30, 0x80080
	s_addc_u32 s31, s31, 0
	s_add_i32 s34, s34, s44
	v_lshl_add_u64 v[150:151], s[30:31], 0, v[132:133]
	s_mov_b32 m0, s34
	s_nop 0
	global_load_lds_dwordx4 v[150:151], off
	v_lshl_add_u64 v[150:151], s[30:31], 0, v[136:137]
	s_add_i32 m0, s34, 0x2000
	s_nop 0
	global_load_lds_dwordx4 v[150:151], off
	s_waitcnt vmcnt(6)
	s_barrier
	s_setprio 1
	v_mfma_f32_16x16x32_bf16 v[54:57], v[206:209], v[174:177], v[54:57]
	v_mfma_f32_16x16x32_bf16 v[50:53], v[214:217], v[174:177], v[50:53]
	v_mfma_f32_16x16x32_bf16 v[38:41], v[206:209], v[182:185], v[38:41]
	v_mfma_f32_16x16x32_bf16 v[34:37], v[214:217], v[182:185], v[34:37]
	v_mfma_f32_16x16x32_bf16 v[22:25], v[206:209], v[190:193], v[22:25]
	v_mfma_f32_16x16x32_bf16 v[18:21], v[214:217], v[190:193], v[18:21]
	v_mfma_f32_16x16x32_bf16 v[6:9], v[206:209], v[198:201], v[6:9]
	v_mfma_f32_16x16x32_bf16 v[2:5], v[214:217], v[198:201], v[2:5]
	v_mfma_f32_16x16x32_bf16 v[54:57], v[210:213], v[178:181], v[54:57]
	v_mfma_f32_16x16x32_bf16 v[50:53], v[218:221], v[178:181], v[50:53]
	v_mfma_f32_16x16x32_bf16 v[38:41], v[210:213], v[186:189], v[38:41]
	v_mfma_f32_16x16x32_bf16 v[34:37], v[218:221], v[186:189], v[34:37]
	v_mfma_f32_16x16x32_bf16 v[22:25], v[210:213], v[194:197], v[22:25]
	v_mfma_f32_16x16x32_bf16 v[18:21], v[218:221], v[194:197], v[18:21]
	v_mfma_f32_16x16x32_bf16 v[6:9], v[210:213], v[202:205], v[6:9]
	v_mfma_f32_16x16x32_bf16 v[2:5], v[218:221], v[202:205], v[2:5]
	s_setprio 0
	s_add_i32 s39, s39, 2
	s_add_u32 s6, s6, 0x100
	s_addc_u32 s7, s7, 0
	s_add_u32 s37, s37, 0x100
	s_addc_u32 s38, s38, 0
	s_cmp_gt_u32 s39, 29
	s_barrier
	s_cbranch_scc0 .LBB0_184
	v_lshl_add_u32 v150, s4, 8, v164
	v_ashrrev_i32_e32 v151, 31, v150
	v_lshl_add_u64 v[152:153], v[150:151], 2, s[12:13]
	s_nop 0
	s_cmp_lt_i32 s36, 4
	s_cselect_b64 s[34:35], -1, 0
	s_cmp_gt_i32 s36, 3
	s_cselect_b64 s[4:5], -1, 0
	s_cmp_gt_u32 s36, 15
	s_cselect_b64 s[38:39], -1, 0
	s_lshl_b32 s30, s36, 8
	v_mad_i64_i32 v[154:155], s[6:7], v150, s57, 0
	s_mov_b32 s8, s30
	v_lshlrev_b64 v[156:157], 9, v[150:151]
	s_mov_b64 s[6:7], -1
	s_and_b64 vcc, exec, s[4:5]
	s_cbranch_vccz .LBB0_191
	s_and_b64 vcc, exec, s[38:39]
	s_cbranch_vccz .LBB0_188
	v_lshl_add_u64 v[162:163], s[14:15], 0, v[156:157]
	s_mov_b64 s[6:7], 0

;   DI void operator()(const f32x4 (&acc)[2][2][4][2], const pg8::Unit& u, int wr, int wc, int fr, int fq) const {
;     ...
;           f32x4 v0 = acc[ai][bj][m][0] * rs, v1 = acc[ai][bj][m][1] * rs;
;           if (MODE == EP_IN || MODE == EP_MIX || MODE == EP_DOWN) {
; #pragma unroll
;             for (int j = 0; j < 4; ++j) ssq += v0[j] * v0[j] + v1[j] * v1[j];
;           }
;           if (MODE == EP_UP) {
; #pragma unroll
;             for (int j = 0; j < 4; ++j) { float a = fmaxf(v0[j], 0.f), b = fmaxf(v1[j], 0.f); v0[j] = a * a; v1[j] = b * b; }
;           }
;           bf16_t* dst;
;           const int ct = bj * 128 + cl;
;           if (MODE == EP_IN) {
;             if (pn < 4) dst = (bf16_t*)(ws + OFF_PROJA) + (size_t)grow * 1024 + pn * 256 + ct;
;             else if (pn < 16) dst = (bf16_t*)(ws + OFF_PROJG) + (size_t)grow * 3072 + (pn - 4) * 256 + ct;
;             else dst = (bf16_t*)(ws + OFF_PROJS) + (size_t)grow * 256 + ct;
;           } else if (MODE == EP_Q) {
;             if (pn < 4) dst = (bf16_t*)(dout + DO_Q) + (size_t)grow * 1536 + (pn * 2 + bj) * 192 + cl;
;             else {
;               const int mm = (pn - 4) * 256 + ct, h = mm >> 6, r = mm & 63;
;               dst = (bf16_t*)(dout + DO_Q) + (size_t)grow * 1536 + h * 192 + 128 + r;
;               const int pos = grow < TP ? (grow & 4095) : grow - TP;
;               const f32x4* tb = (const f32x4*)((const f32x2*)(ws + OFF_ROPE) + pos * 32 + (r >> 1));
;               const f32x4 t0 = tb[0], t1 = tb[1];
;               f32x4 o0, o1;
;               o0[0] = v0[0] * t0[0] - v0[1] * t0[1]; o0[1] = v0[1] * t0[0] + v0[0] * t0[1];
;               o0[2] = v0[2] * t0[2] - v0[3] * t0[3]; o0[3] = v0[3] * t0[2] + v0[2] * t0[3];
;               o1[0] = v1[0] * t1[0] - v1[1] * t1[1]; o1[1] = v1[1] * t1[0] + v1[0] * t1[1];
;               o1[2] = v1[2] * t1[2] - v1[3] * t1[3]; o1[3] = v1[3] * t1[2] + v1[2] * t1[3];
;               v0 = o0; v1 = o1;
;             }
;           } else if (MODE == EP_KV) {
;             dst = (bf16_t*)(ws + OFF_XB) + (size_t)grow * 2048 + pn * 256 + ct;
;           } else if (MODE == EP_MIX) {
;             dst = (bf16_t*)(ws + OFF_MIX) + (size_t)grow * 2048 + pn * 256 + ct;
;           } else if (MODE == EP_UP) {
;             dst = (bf16_t*)(ws + OFF_U) + (size_t)row * 8192 + pn * 256 + ct;
;           } else {
.LBB0_193:
	v_mov_b32_e32 v152, v247
	v_pk_mul_f32 v[128:129], v[128:129], v[152:153] op_sel_hi:[1,0]
	v_pk_mul_f32 v[126:127], v[126:127], v[152:153] op_sel_hi:[1,0]
	v_pk_mul_f32 v[124:125], v[124:125], v[152:153] op_sel_hi:[1,0]
	v_pk_mul_f32 v[160:161], v[122:123], v[152:153] op_sel_hi:[1,0]
	v_lshlrev_b32_e32 v138, 1, v140
	v_lshl_add_u64 v[122:123], v[162:163], 0, v[138:139]
	v_cvt_pk_bf16_f32 v170, v126, v127
	v_cvt_pk_bf16_f32 v171, v128, v129
	v_cvt_pk_bf16_f32 v172, v160, v161
	v_cvt_pk_bf16_f32 v173, v124, v125
	global_store_dwordx4 v[122:123], v[170:173], off
	v_cndmask_b32_e64 v122, 0, 1, s[4:5]
	v_cmp_ne_u32_e64 s[6:7], 1, v122
	v_cndmask_b32_e64 v122, 0, 1, s[38:39]
	s_mov_b64 s[40:41], -1
	s_andn2_b64 vcc, exec, s[4:5]
	v_cmp_ne_u32_e64 s[4:5], 1, v122
	s_cbranch_vccnz .LBB0_199
	s_and_b64 vcc, exec, s[4:5]
	s_mov_b64 s[38:39], -1
	s_cbranch_vccnz .LBB0_196
	v_lshl_add_u64 v[122:123], s[14:15], 0, v[156:157]
	s_mov_b64 s[38:39], 0

;   DI bool next(int i, Unit& u) const {
;     const long L = (long)i * G + c; if (L >= nwg) return false;
;     int wgid = (int)L; { const int q = nwg / NXCD, r = nwg % NXCD, xcd = wgid % NXCD, off = wgid / NXCD; wgid = (xcd < r ? xcd * (q + 1) : r * (q + 1) + (xcd - r) * q) + off; }
;     const int nig = wgm * nN, gid = wgid / nig, fm = gid * wgm, gsz = (nM - fm) < wgm ? (nM - fm) : wgm;
;     u.pm = fm + ((wgid % nig) % gsz); u.pn = (wgid % nig) / gsz; return true;
;   }
;   DI void operator()(const f32x4 (&acc)[2][2][4][2], const pg8::Unit& u, int wr, int wc, int fr, int fq) const {
;     ...
;         const int row = u.pm * 256 + ai * 128 + wr * 64 + m * 16 + fr;
;         const int grow = rowbase + row;
;         float rs = 1.f;
;         if (MODE == EP_IN) rs = ((const float*)(ws + OFF_RS0))[grow];
;         if (MODE == EP_UP) rs = ((const float*)(ws + OFF_RS2))[grow];
.LBB0_914:
	v_lshl_add_u32 v248, s16, 8, v1
	v_ashrrev_i32_e32 v249, 31, v248
	v_lshl_add_u64 v[248:249], v[248:249], 2, s[4:5]
	global_load_dword v247, v[248:249], off
	global_load_dword v240, v[248:249], off offset:64
	global_load_dword v241, v[248:249], off offset:128
	global_load_dword v242, v[248:249], off offset:192
	global_load_dword v243, v[248:249], off offset:512
	global_load_dword v244, v[248:249], off offset:576
	global_load_dword v245, v[248:249], off offset:640
	global_load_dword v246, v[248:249], off offset:704
	s_add_i32 s35, s35, 1
	s_mul_i32 s0, s35, s38
	s_mul_hi_u32 s1, s35, s68
	s_add_i32 s1, s1, s0
	s_mul_i32 s0, s35, s68
	s_add_u32 s12, s0, s60
	s_addc_u32 s13, s1, s25
	v_cmp_gt_i64_e64 s[0:1], s[12:13], v[146:147]
	s_and_b64 vcc, exec, s[0:1]
	s_cbranch_vccnz .LBB0_920
	s_ashr_i32 s8, s12, 31
	s_lshr_b32 s8, s8, 29
	s_add_i32 s10, s12, s8
	s_and_b32 s8, s10, -8
	s_sub_i32 s11, s12, s8
	s_cmp_gt_i32 s11, -1
	s_mov_b64 s[8:9], -1
	s_cbranch_scc0 .LBB0_917
	s_lshl_b32 s14, s11, 8
	s_mov_b64 s[8:9], 0

; #define PG8_STAGE(bufoff, gbase, voff) do { _Pragma("unroll") for (int _i = 0; _i < 2; ++_i) \
;     __builtin_amdgcn_global_load_lds((const unsigned*)((const char*)(gbase) + (voff)[_i]), (LAS unsigned*)(lds + (bufoff) + ldsw + _i * 8192), 16, 0, 0); } while (0)
; #define PG8_LDA(dst, b, h) do { _Pragma("unroll") for (int m = 0; m < 4; ++m) _Pragma("unroll") for (int k = 0; k < 2; ++k) dst[m][k] = *(const LAS bf16x8*)(lds + PG8_SA(b, h) + aoff + m * 2048 + k * 1024); } while (0)
; #define PG8_LDB(dst, b, h) do { _Pragma("unroll") for (int n = 0; n < 2; ++n) _Pragma("unroll") for (int k = 0; k < 2; ++k) dst[n][k] = *(const LAS bf16x8*)(lds + PG8_SB(b, h) + boff + n * 2048 + k * 1024); } while (0)
; #define PG8_MMA(ai, bj, At, Bt) do { __builtin_amdgcn_s_setprio(1); _Pragma("unroll") for (int m = 0; m < 4; ++m) _Pragma("unroll") for (int n = 0; n < 2; ++n) _Pragma("unroll") for (int k = 0; k < 2; ++k) \
;     acc[ai][bj][m][n] = __builtin_amdgcn_mfma_f32_16x16x32_bf16(Bt[n][k], At[m][k], acc[ai][bj][m][n], 0, 0, 0); __builtin_amdgcn_s_setprio(0); } while (0)
; #define PG8_WAIT_L(n) asm volatile("s_waitcnt lgkmcnt(" #n ")" ::: "memory")
; #define PG8_BAR __builtin_amdgcn_s_barrier()
; #define PG8_SCHED __builtin_amdgcn_sched_barrier(0)
; template <class Epi>
; DI void gemm_phase(LAS unsigned char* lds, const Gemm g, const StaticOrder& S, const Epi& E) {
;     ...
;       PG8_LDB(B0, 0, 0); PG8_SCHED; PG8_LDA(At, 0, 0); PG8_STAGE(PG8_SA(1, 1), a1 + hstepA, voffA);
;       PG8_WAIT_L(8); PG8_BAR; PG8_WAIT_L(0); PG8_MMA(0, 0, At, B0); PG8_BAR; PG8_SCHED;
;       PG8_LDB(B1, 0, 1); PG8_STAGE(PG8_SB(0, 0), b2, voffB);
;       PG8_BAR; PG8_WAIT_L(0); PG8_MMA(0, 1, At, B1); PG8_BAR;
;       PG8_LDA(At, 0, 1); PG8_STAGE(PG8_SA(0, 0), a2, voffA);
;       PG8_BAR; PG8_WAIT_L(0); PG8_MMA(1, 0, At, B0); PG8_BAR; PG8_SCHED;
.LBB0_921:
	ds_read_b128 v[154:157], v151
	ds_read_b128 v[158:161], v151 offset:1024
	ds_read_b128 v[162:165], v151 offset:2048
	ds_read_b128 v[166:169], v151 offset:3072
	s_add_u32 s20, s18, 0xfff80080
	s_addc_u32 s21, s19, -1
	s_cmp_eq_u32 s46, 28
	s_cselect_b32 s23, s11, s21
	s_cselect_b32 s22, s42, s20
	s_cselect_b32 s21, s9, s45
	s_cselect_b32 s20, s43, s44
	v_lshl_add_u64 v[148:149], s[18:19], 0, v[140:141]
	s_add_i32 m0, s17, 0xc000
	ds_read_b128 v[170:173], v152
	ds_read_b128 v[174:177], v152 offset:1024
	ds_read_b128 v[178:181], v152 offset:2048
	ds_read_b128 v[182:185], v152 offset:3072
	ds_read_b128 v[186:189], v152 offset:4096
	ds_read_b128 v[190:193], v152 offset:5120
	ds_read_b128 v[194:197], v152 offset:6144
	ds_read_b128 v[198:201], v152 offset:7168
	global_load_lds_dwordx4 v[148:149], off
	v_lshl_add_u64 v[148:149], s[18:19], 0, v[142:143]
	s_add_i32 m0, s17, 0xe000
	s_nop 0
	global_load_lds_dwordx4 v[148:149], off
	s_waitcnt lgkmcnt(8)
	s_barrier
	s_waitcnt lgkmcnt(0)
	s_setprio 1
	s_waitcnt lgkmcnt(0)
	v_mfma_f32_16x16x32_bf16 v[126:129], v[154:157], v[170:173], v[126:129]
	v_mfma_f32_16x16x32_bf16 v[122:125], v[162:165], v[170:173], v[122:125]
	v_mfma_f32_16x16x32_bf16 v[110:113], v[154:157], v[178:181], v[110:113]
	v_mfma_f32_16x16x32_bf16 v[106:109], v[162:165], v[178:181], v[106:109]
	v_mfma_f32_16x16x32_bf16 v[94:97], v[154:157], v[186:189], v[94:97]
	v_mfma_f32_16x16x32_bf16 v[90:93], v[162:165], v[186:189], v[90:93]
	v_mfma_f32_16x16x32_bf16 v[78:81], v[154:157], v[194:197], v[78:81]
	v_mfma_f32_16x16x32_bf16 v[74:77], v[162:165], v[194:197], v[74:77]
	v_mfma_f32_16x16x32_bf16 v[126:129], v[158:161], v[174:177], v[126:129]
	v_mfma_f32_16x16x32_bf16 v[122:125], v[166:169], v[174:177], v[122:125]
	v_mfma_f32_16x16x32_bf16 v[110:113], v[158:161], v[182:185], v[110:113]
	v_mfma_f32_16x16x32_bf16 v[106:109], v[166:169], v[182:185], v[106:109]
	v_mfma_f32_16x16x32_bf16 v[94:97], v[158:161], v[190:193], v[94:97]
	v_mfma_f32_16x16x32_bf16 v[90:93], v[166:169], v[190:193], v[90:93]
	v_mfma_f32_16x16x32_bf16 v[78:81], v[158:161], v[198:201], v[78:81]
	v_mfma_f32_16x16x32_bf16 v[74:77], v[166:169], v[198:201], v[74:77]
	s_setprio 0
	s_barrier
	s_add_i32 s47, s39, s30
	v_lshl_add_u64 v[148:149], s[20:21], 0, v[132:133]
	s_mov_b32 m0, s47
	ds_read_b128 v[202:205], v153
	ds_read_b128 v[206:209], v153 offset:1024
	ds_read_b128 v[210:213], v153 offset:2048
	ds_read_b128 v[214:217], v153 offset:3072
	global_load_lds_dwordx4 v[148:149], off
	v_lshl_add_u64 v[218:219], s[20:21], 0, v[136:137]
	s_add_i32 m0, s47, 0x2000
	s_nop 0
	global_load_lds_dwordx4 v[218:219], off
	s_barrier
	s_waitcnt lgkmcnt(0)
	s_setprio 1
	s_waitcnt lgkmcnt(0)
	v_mfma_f32_16x16x32_bf16 v[118:121], v[202:205], v[170:173], v[118:121]
	v_mfma_f32_16x16x32_bf16 v[114:117], v[210:213], v[170:173], v[114:117]
	v_mfma_f32_16x16x32_bf16 v[102:105], v[202:205], v[178:181], v[102:105]
	v_mfma_f32_16x16x32_bf16 v[98:101], v[210:213], v[178:181], v[98:101]
	v_mfma_f32_16x16x32_bf16 v[86:89], v[202:205], v[186:189], v[86:89]
	v_mfma_f32_16x16x32_bf16 v[82:85], v[210:213], v[186:189], v[82:85]
	v_mfma_f32_16x16x32_bf16 v[70:73], v[202:205], v[194:197], v[70:73]
	v_mfma_f32_16x16x32_bf16 v[66:69], v[210:213], v[194:197], v[66:69]
	v_mfma_f32_16x16x32_bf16 v[118:121], v[206:209], v[174:177], v[118:121]
	v_mfma_f32_16x16x32_bf16 v[114:117], v[214:217], v[174:177], v[114:117]
	v_mfma_f32_16x16x32_bf16 v[102:105], v[206:209], v[182:185], v[102:105]
	v_mfma_f32_16x16x32_bf16 v[98:101], v[214:217], v[182:185], v[98:101]
	v_mfma_f32_16x16x32_bf16 v[86:89], v[206:209], v[190:193], v[86:89]
	v_mfma_f32_16x16x32_bf16 v[82:85], v[214:217], v[190:193], v[82:85]
	v_mfma_f32_16x16x32_bf16 v[70:73], v[206:209], v[198:201], v[70:73]
	v_mfma_f32_16x16x32_bf16 v[66:69], v[214:217], v[198:201], v[66:69]
	s_setprio 0
	s_mov_b32 m0, s17
	v_lshl_add_u64 v[220:221], s[22:23], 0, v[130:131]
	s_barrier
	ds_read_b128 v[170:173], v152 offset:16384
	ds_read_b128 v[174:177], v152 offset:17408
	ds_read_b128 v[178:181], v152 offset:18432
	ds_read_b128 v[182:185], v152 offset:19456
	ds_read_b128 v[186:189], v152 offset:20480
	ds_read_b128 v[190:193], v152 offset:21504
	ds_read_b128 v[194:197], v152 offset:22528
	ds_read_b128 v[198:201], v152 offset:23552
	global_load_lds_dwordx4 v[220:221], off
	v_lshl_add_u64 v[222:223], s[22:23], 0, v[134:135]
	s_mov_b32 m0, s31
	s_nop 0
	global_load_lds_dwordx4 v[222:223], off
	s_barrier
	s_waitcnt lgkmcnt(0)
	s_setprio 1
	s_waitcnt lgkmcnt(0)
	v_mfma_f32_16x16x32_bf16 v[62:65], v[154:157], v[170:173], v[62:65]
	v_mfma_f32_16x16x32_bf16 v[58:61], v[162:165], v[170:173], v[58:61]
	v_mfma_f32_16x16x32_bf16 v[46:49], v[154:157], v[178:181], v[46:49]
	v_mfma_f32_16x16x32_bf16 v[42:45], v[162:165], v[178:181], v[42:45]
	v_mfma_f32_16x16x32_bf16 v[30:33], v[154:157], v[186:189], v[30:33]
	v_mfma_f32_16x16x32_bf16 v[26:29], v[162:165], v[186:189], v[26:29]
	v_mfma_f32_16x16x32_bf16 v[14:17], v[154:157], v[194:197], v[14:17]
	v_mfma_f32_16x16x32_bf16 v[10:13], v[162:165], v[194:197], v[10:13]
	v_mfma_f32_16x16x32_bf16 v[62:65], v[158:161], v[174:177], v[62:65]
	v_mfma_f32_16x16x32_bf16 v[58:61], v[166:169], v[174:177], v[58:61]
	v_mfma_f32_16x16x32_bf16 v[46:49], v[158:161], v[182:185], v[46:49]
	v_mfma_f32_16x16x32_bf16 v[42:45], v[166:169], v[182:185], v[42:45]
	v_mfma_f32_16x16x32_bf16 v[30:33], v[158:161], v[190:193], v[30:33]
	v_mfma_f32_16x16x32_bf16 v[26:29], v[166:169], v[190:193], v[26:29]
	v_mfma_f32_16x16x32_bf16 v[14:17], v[158:161], v[198:201], v[14:17]
	v_mfma_f32_16x16x32_bf16 v[10:13], v[166:169], v[198:201], v[10:13]
	s_setprio 0
	s_barrier
; #define PG8_STAGE(bufoff, gbase, voff) do { _Pragma("unroll") for (int _i = 0; _i < 2; ++_i) \
;     __builtin_amdgcn_global_load_lds((const unsigned*)((const char*)(gbase) + (voff)[_i]), (LAS unsigned*)(lds + (bufoff) + ldsw + _i * 8192), 16, 0, 0); } while (0)
; #define PG8_LDA(dst, b, h) do { _Pragma("unroll") for (int m = 0; m < 4; ++m) _Pragma("unroll") for (int k = 0; k < 2; ++k) dst[m][k] = *(const LAS bf16x8*)(lds + PG8_SA(b, h) + aoff + m * 2048 + k * 1024); } while (0)
; #define PG8_LDB(dst, b, h) do { _Pragma("unroll") for (int n = 0; n < 2; ++n) _Pragma("unroll") for (int k = 0; k < 2; ++k) dst[n][k] = *(const LAS bf16x8*)(lds + PG8_SB(b, h) + boff + n * 2048 + k * 1024); } while (0)
; #define PG8_MMA(ai, bj, At, Bt) do { __builtin_amdgcn_s_setprio(1); _Pragma("unroll") for (int m = 0; m < 4; ++m) _Pragma("unroll") for (int n = 0; n < 2; ++n) _Pragma("unroll") for (int k = 0; k < 2; ++k) \
;     acc[ai][bj][m][n] = __builtin_amdgcn_mfma_f32_16x16x32_bf16(Bt[n][k], At[m][k], acc[ai][bj][m][n], 0, 0, 0); __builtin_amdgcn_s_setprio(0); } while (0)
; #define PG8_WAIT_V(n) asm volatile("s_waitcnt vmcnt(" #n ")" ::: "memory")
; #define PG8_WAIT_L(n) asm volatile("s_waitcnt lgkmcnt(" #n ")" ::: "memory")
; #define PG8_BAR __builtin_amdgcn_s_barrier()
; #define PG8_SCHED __builtin_amdgcn_sched_barrier(0)
; template <class Epi>
; DI void gemm_phase(LAS unsigned char* lds, const Gemm g, const StaticOrder& S, const Epi& E) {
;     ...
;       PG8_STAGE(PG8_SB(0, 1), b2 + hstepB, voffB);
;       PG8_WAIT_V(6); PG8_BAR; PG8_MMA(1, 1, At, B1); PG8_BAR;
;       PG8_LDB(B0, 1, 0); PG8_SCHED; PG8_LDA(At, 1, 0); PG8_STAGE(PG8_SA(0, 1), a2 + hstepA, voffA);
;       PG8_WAIT_L(8); PG8_BAR; PG8_WAIT_L(0); PG8_MMA(0, 0, At, B0); PG8_BAR; PG8_SCHED;
;       PG8_LDB(B1, 1, 1); PG8_STAGE(PG8_SB(1, 0), b3, voffB);
;       PG8_BAR; PG8_WAIT_L(0); PG8_MMA(0, 1, At, B1); PG8_BAR;
;       PG8_LDA(At, 1, 1); PG8_STAGE(PG8_SA(1, 0), a3, voffA);
	s_add_u32 s48, s20, 0x80000
	s_addc_u32 s49, s21, 0
	s_add_i32 s47, s40, s30
	v_lshl_add_u64 v[154:155], s[48:49], 0, v[132:133]
	s_mov_b32 m0, s47
	s_nop 0
	global_load_lds_dwordx4 v[154:155], off
	v_lshl_add_u64 v[154:155], s[48:49], 0, v[136:137]
	s_add_i32 m0, s47, 0x2000
	s_nop 0
	global_load_lds_dwordx4 v[154:155], off
	s_waitcnt vmcnt(6)
	s_barrier
	s_setprio 1
	v_mfma_f32_16x16x32_bf16 v[54:57], v[202:205], v[170:173], v[54:57]
	v_mfma_f32_16x16x32_bf16 v[50:53], v[210:213], v[170:173], v[50:53]
	v_mfma_f32_16x16x32_bf16 v[38:41], v[202:205], v[178:181], v[38:41]
	v_mfma_f32_16x16x32_bf16 v[34:37], v[210:213], v[178:181], v[34:37]
	v_mfma_f32_16x16x32_bf16 v[22:25], v[202:205], v[186:189], v[22:25]
	v_mfma_f32_16x16x32_bf16 v[18:21], v[210:213], v[186:189], v[18:21]
	v_mfma_f32_16x16x32_bf16 v[6:9], v[202:205], v[194:197], v[6:9]
	v_mfma_f32_16x16x32_bf16 v[2:5], v[210:213], v[194:197], v[2:5]
	v_mfma_f32_16x16x32_bf16 v[54:57], v[206:209], v[174:177], v[54:57]
	v_mfma_f32_16x16x32_bf16 v[50:53], v[214:217], v[174:177], v[50:53]
	v_mfma_f32_16x16x32_bf16 v[38:41], v[206:209], v[182:185], v[38:41]
	v_mfma_f32_16x16x32_bf16 v[34:37], v[214:217], v[182:185], v[34:37]
	v_mfma_f32_16x16x32_bf16 v[22:25], v[206:209], v[190:193], v[22:25]
	v_mfma_f32_16x16x32_bf16 v[18:21], v[214:217], v[190:193], v[18:21]
	v_mfma_f32_16x16x32_bf16 v[6:9], v[206:209], v[198:201], v[6:9]
	v_mfma_f32_16x16x32_bf16 v[2:5], v[214:217], v[198:201], v[2:5]
	s_setprio 0
	s_add_i32 s47, 0, 0x18000
	v_add_u32_e32 v166, s47, v150
	s_barrier
	ds_read_b128 v[154:157], v166
	ds_read_b128 v[158:161], v166 offset:1024
	ds_read_b128 v[162:165], v166 offset:2048
	ds_read_b128 v[166:169], v166 offset:3072
	s_add_u32 s22, s22, 0x80000
	s_addc_u32 s23, s23, 0
	s_mov_b32 m0, s33
	v_lshl_add_u64 v[202:203], s[22:23], 0, v[130:131]
	ds_read_b128 v[170:173], v152 offset:32768
	ds_read_b128 v[174:177], v152 offset:33792
	ds_read_b128 v[178:181], v152 offset:34816
	ds_read_b128 v[182:185], v152 offset:35840
	ds_read_b128 v[186:189], v152 offset:36864
	ds_read_b128 v[190:193], v152 offset:37888
	ds_read_b128 v[194:197], v152 offset:38912
	ds_read_b128 v[198:201], v152 offset:39936
	global_load_lds_dwordx4 v[202:203], off
	v_lshl_add_u64 v[202:203], s[22:23], 0, v[134:135]
	s_mov_b32 m0, s34
	s_nop 0
	global_load_lds_dwordx4 v[202:203], off
	s_waitcnt lgkmcnt(8)
	s_barrier
	s_waitcnt lgkmcnt(0)
	s_setprio 1
	s_waitcnt lgkmcnt(0)
	v_mfma_f32_16x16x32_bf16 v[126:129], v[154:157], v[170:173], v[126:129]
	v_mfma_f32_16x16x32_bf16 v[122:125], v[162:165], v[170:173], v[122:125]
	v_mfma_f32_16x16x32_bf16 v[110:113], v[154:157], v[178:181], v[110:113]
	v_mfma_f32_16x16x32_bf16 v[106:109], v[162:165], v[178:181], v[106:109]
	v_mfma_f32_16x16x32_bf16 v[94:97], v[154:157], v[186:189], v[94:97]
	v_mfma_f32_16x16x32_bf16 v[90:93], v[162:165], v[186:189], v[90:93]
	v_mfma_f32_16x16x32_bf16 v[78:81], v[154:157], v[194:197], v[78:81]
	v_mfma_f32_16x16x32_bf16 v[74:77], v[162:165], v[194:197], v[74:77]
	v_mfma_f32_16x16x32_bf16 v[126:129], v[158:161], v[174:177], v[126:129]
	v_mfma_f32_16x16x32_bf16 v[122:125], v[166:169], v[174:177], v[122:125]
	v_mfma_f32_16x16x32_bf16 v[110:113], v[158:161], v[182:185], v[110:113]
	v_mfma_f32_16x16x32_bf16 v[106:109], v[166:169], v[182:185], v[106:109]
	v_mfma_f32_16x16x32_bf16 v[94:97], v[158:161], v[190:193], v[94:97]
	v_mfma_f32_16x16x32_bf16 v[90:93], v[166:169], v[190:193], v[90:93]
	v_mfma_f32_16x16x32_bf16 v[78:81], v[158:161], v[198:201], v[78:81]
	v_mfma_f32_16x16x32_bf16 v[74:77], v[166:169], v[198:201], v[74:77]
	s_setprio 0
	s_barrier
	s_add_i32 s22, 0, 0x1c000
	s_add_i32 s23, s47, s30
	v_add_u32_e32 v214, s22, v150
	v_lshl_add_u64 v[148:149], v[148:149], 0, s[2:3]
	s_mov_b32 m0, s23
	ds_read_b128 v[202:205], v214
	ds_read_b128 v[206:209], v214 offset:1024
	ds_read_b128 v[210:213], v214 offset:2048
	ds_read_b128 v[214:217], v214 offset:3072
	global_load_lds_dwordx4 v[148:149], off
	v_lshl_add_u64 v[148:149], v[218:219], 0, s[2:3]
	s_add_i32 m0, s23, 0x2000
	s_nop 0
	global_load_lds_dwordx4 v[148:149], off
	s_barrier
	s_waitcnt lgkmcnt(0)
	s_setprio 1
	s_waitcnt lgkmcnt(0)
	v_mfma_f32_16x16x32_bf16 v[118:121], v[202:205], v[170:173], v[118:121]
	v_mfma_f32_16x16x32_bf16 v[114:117], v[210:213], v[170:173], v[114:117]
	v_mfma_f32_16x16x32_bf16 v[102:105], v[202:205], v[178:181], v[102:105]
	v_mfma_f32_16x16x32_bf16 v[98:101], v[210:213], v[178:181], v[98:101]
	v_mfma_f32_16x16x32_bf16 v[86:89], v[202:205], v[186:189], v[86:89]
	v_mfma_f32_16x16x32_bf16 v[82:85], v[210:213], v[186:189], v[82:85]
	v_mfma_f32_16x16x32_bf16 v[70:73], v[202:205], v[194:197], v[70:73]
	v_mfma_f32_16x16x32_bf16 v[66:69], v[210:213], v[194:197], v[66:69]
	v_mfma_f32_16x16x32_bf16 v[118:121], v[206:209], v[174:177], v[118:121]
	v_mfma_f32_16x16x32_bf16 v[114:117], v[214:217], v[174:177], v[114:117]
	v_mfma_f32_16x16x32_bf16 v[102:105], v[206:209], v[182:185], v[102:105]
	v_mfma_f32_16x16x32_bf16 v[98:101], v[214:217], v[182:185], v[98:101]
	v_mfma_f32_16x16x32_bf16 v[86:89], v[206:209], v[190:193], v[86:89]
	v_mfma_f32_16x16x32_bf16 v[82:85], v[214:217], v[190:193], v[82:85]
	v_mfma_f32_16x16x32_bf16 v[70:73], v[206:209], v[198:201], v[70:73]
	v_mfma_f32_16x16x32_bf16 v[66:69], v[214:217], v[198:201], v[66:69]
	s_setprio 0
	s_mov_b32 m0, s36
	v_lshl_add_u64 v[148:149], v[220:221], 0, s[2:3]
	s_barrier
	ds_read_b128 v[170:173], v152 offset:49152
	ds_read_b128 v[174:177], v152 offset:50176
	ds_read_b128 v[178:181], v152 offset:51200
	ds_read_b128 v[182:185], v152 offset:52224
	ds_read_b128 v[186:189], v152 offset:53248
	ds_read_b128 v[190:193], v152 offset:54272
	ds_read_b128 v[194:197], v152 offset:55296
	ds_read_b128 v[198:201], v152 offset:56320
	global_load_lds_dwordx4 v[148:149], off
	v_lshl_add_u64 v[148:149], v[222:223], 0, s[2:3]
	s_mov_b32 m0, s37
	s_nop 0
	global_load_lds_dwordx4 v[148:149], off
	s_barrier
; template <class Epi>
; DI void gemm_phase(LAS unsigned char* lds, const Gemm g, const StaticOrder& S, const Epi& E) {
;     ...
;       PG8_LDA(At, 1, 1); PG8_STAGE(PG8_SA(1, 0), a3, voffA);
;       PG8_BAR; PG8_WAIT_L(0); PG8_MMA(1, 0, At, B0); PG8_BAR; PG8_SCHED;
;       PG8_STAGE(PG8_SB(1, 1), b3 + hstepB, voffB);
;       PG8_WAIT_V(6); PG8_BAR; PG8_MMA(1, 1, At, B1); PG8_BAR;
;     }
;     E(acc, cur, wr, wc, fr, fq);
;   DI void operator()(const f32x4 (&acc)[2][2][4][2], const pg8::Unit& u, int wr, int wc, int fr, int fq) const {
;     ...
;           f32x4 v0 = acc[ai][bj][m][0] * rs, v1 = acc[ai][bj][m][1] * rs;
;           if (MODE == EP_IN || MODE == EP_MIX || MODE == EP_DOWN) {
; #pragma unroll
;             for (int j = 0; j < 4; ++j) ssq += v0[j] * v0[j] + v1[j] * v1[j];
;           }
;           if (MODE == EP_UP) {
; #pragma unroll
;             for (int j = 0; j < 4; ++j) { float a = fmaxf(v0[j], 0.f), b = fmaxf(v1[j], 0.f); v0[j] = a * a; v1[j] = b * b; }
;           }
;           bf16_t* dst;
;           const int ct = bj * 128 + cl;
;           if (MODE == EP_IN) {
;             if (pn < 4) dst = (bf16_t*)(ws + OFF_PROJA) + (size_t)grow * 1024 + pn * 256 + ct;
;             else if (pn < 16) dst = (bf16_t*)(ws + OFF_PROJG) + (size_t)grow * 3072 + (pn - 4) * 256 + ct;
;             else dst = (bf16_t*)(ws + OFF_PROJS) + (size_t)grow * 256 + ct;
;           } else if (MODE == EP_Q) {
;             if (pn < 4) dst = (bf16_t*)(dout + DO_Q) + (size_t)grow * 1536 + (pn * 2 + bj) * 192 + cl;
;             else {
;               const int mm = (pn - 4) * 256 + ct, h = mm >> 6, r = mm & 63;
;               dst = (bf16_t*)(dout + DO_Q) + (size_t)grow * 1536 + h * 192 + 128 + r;
;               const int pos = grow < TP ? (grow & 4095) : grow - TP;
;               const f32x4* tb = (const f32x4*)((const f32x2*)(ws + OFF_ROPE) + pos * 32 + (r >> 1));
;               const f32x4 t0 = tb[0], t1 = tb[1];
;               f32x4 o0, o1;
;               o0[0] = v0[0] * t0[0] - v0[1] * t0[1]; o0[1] = v0[1] * t0[0] + v0[0] * t0[1];
;               o0[2] = v0[2] * t0[2] - v0[3] * t0[3]; o0[3] = v0[3] * t0[2] + v0[2] * t0[3];
;               o1[0] = v1[0] * t1[0] - v1[1] * t1[1]; o1[1] = v1[1] * t1[0] + v1[0] * t1[1];
;               o1[2] = v1[2] * t1[2] - v1[3] * t1[3]; o1[3] = v1[3] * t1[2] + v1[2] * t1[3];
;               v0 = o0; v1 = o1;
;             }
	s_waitcnt lgkmcnt(0)
	s_setprio 1
	s_waitcnt lgkmcnt(0)
	v_mfma_f32_16x16x32_bf16 v[62:65], v[154:157], v[170:173], v[62:65]
	v_mfma_f32_16x16x32_bf16 v[58:61], v[162:165], v[170:173], v[58:61]
	v_mfma_f32_16x16x32_bf16 v[46:49], v[154:157], v[178:181], v[46:49]
	v_mfma_f32_16x16x32_bf16 v[42:45], v[162:165], v[178:181], v[42:45]
	v_mfma_f32_16x16x32_bf16 v[30:33], v[154:157], v[186:189], v[30:33]
	v_mfma_f32_16x16x32_bf16 v[26:29], v[162:165], v[186:189], v[26:29]
	v_mfma_f32_16x16x32_bf16 v[14:17], v[154:157], v[194:197], v[14:17]
	v_mfma_f32_16x16x32_bf16 v[10:13], v[162:165], v[194:197], v[10:13]
	v_mfma_f32_16x16x32_bf16 v[62:65], v[158:161], v[174:177], v[62:65]
	v_mfma_f32_16x16x32_bf16 v[58:61], v[166:169], v[174:177], v[58:61]
	v_mfma_f32_16x16x32_bf16 v[46:49], v[158:161], v[182:185], v[46:49]
	v_mfma_f32_16x16x32_bf16 v[42:45], v[166:169], v[182:185], v[42:45]
	v_mfma_f32_16x16x32_bf16 v[30:33], v[158:161], v[190:193], v[30:33]
	v_mfma_f32_16x16x32_bf16 v[26:29], v[166:169], v[190:193], v[26:29]
	v_mfma_f32_16x16x32_bf16 v[14:17], v[158:161], v[198:201], v[14:17]
	v_mfma_f32_16x16x32_bf16 v[10:13], v[166:169], v[198:201], v[10:13]
	s_setprio 0
	s_barrier
	s_add_u32 s20, s20, 0x80080
	s_addc_u32 s21, s21, 0
	s_add_i32 s22, s22, s30
	v_lshl_add_u64 v[148:149], s[20:21], 0, v[132:133]
	s_mov_b32 m0, s22
	s_nop 0
	global_load_lds_dwordx4 v[148:149], off
	v_lshl_add_u64 v[148:149], s[20:21], 0, v[136:137]
	s_add_i32 m0, s22, 0x2000
	s_nop 0
	global_load_lds_dwordx4 v[148:149], off
	s_waitcnt vmcnt(6)
	s_barrier
	s_setprio 1
	v_mfma_f32_16x16x32_bf16 v[54:57], v[202:205], v[170:173], v[54:57]
	v_mfma_f32_16x16x32_bf16 v[50:53], v[210:213], v[170:173], v[50:53]
	v_mfma_f32_16x16x32_bf16 v[38:41], v[202:205], v[178:181], v[38:41]
	v_mfma_f32_16x16x32_bf16 v[34:37], v[210:213], v[178:181], v[34:37]
	v_mfma_f32_16x16x32_bf16 v[22:25], v[202:205], v[186:189], v[22:25]
	v_mfma_f32_16x16x32_bf16 v[18:21], v[210:213], v[186:189], v[18:21]
	v_mfma_f32_16x16x32_bf16 v[6:9], v[202:205], v[194:197], v[6:9]
	v_mfma_f32_16x16x32_bf16 v[2:5], v[210:213], v[194:197], v[2:5]
	v_mfma_f32_16x16x32_bf16 v[54:57], v[206:209], v[174:177], v[54:57]
	v_mfma_f32_16x16x32_bf16 v[50:53], v[214:217], v[174:177], v[50:53]
	v_mfma_f32_16x16x32_bf16 v[38:41], v[206:209], v[182:185], v[38:41]
	v_mfma_f32_16x16x32_bf16 v[34:37], v[214:217], v[182:185], v[34:37]
	v_mfma_f32_16x16x32_bf16 v[22:25], v[206:209], v[190:193], v[22:25]
	v_mfma_f32_16x16x32_bf16 v[18:21], v[214:217], v[190:193], v[18:21]
	v_mfma_f32_16x16x32_bf16 v[6:9], v[206:209], v[198:201], v[6:9]
	v_mfma_f32_16x16x32_bf16 v[2:5], v[214:217], v[198:201], v[2:5]
	s_setprio 0
	s_add_i32 s46, s46, 2
	s_add_u32 s18, s18, 0x100
	s_addc_u32 s19, s19, 0
	s_add_u32 s44, s44, 0x100
	s_addc_u32 s45, s45, 0
	s_cmp_gt_u32 s46, 29
	s_barrier
	s_cbranch_scc0 .LBB0_921
	v_lshl_add_u32 v148, s16, 8, v1
	v_ashrrev_i32_e32 v149, 31, v148
	v_lshl_add_u64 v[154:155], v[148:149], 2, s[4:5]
	s_nop 0
	s_lshl_b32 s18, s41, 8
	s_ashr_i32 s19, s18, 31
	v_lshlrev_b64 v[158:159], 14, v[148:149]
	s_lshl_b64 s[18:19], s[18:19], 1
	v_lshl_add_u64 v[158:159], s[6:7], 0, v[158:159]
	v_or_b32_e32 v156, 16, v148
	v_lshl_add_u64 v[158:159], v[158:159], 0, s[18:19]
	v_ashrrev_i32_e32 v157, 31, v156
	v_lshl_add_u64 v[158:159], v[158:159], 0, v[138:139]
	v_lshl_add_u64 v[160:161], v[156:157], 2, s[4:5]
	s_and_b64 vcc, exec, s[0:1]
	s_mov_b32 s41, s8
	s_mov_b32 s16, s10
	s_mov_b64 s[20:21], s[14:15]
	s_mov_b64 s[22:23], s[12:13]
	v_mov_b32_e32 v154, v247
	v_pk_mul_f32 v[128:129], v[128:129], v[154:155] op_sel_hi:[1,0]
	v_pk_mul_f32 v[126:127], v[126:127], v[154:155] op_sel_hi:[1,0]
	v_pk_mul_f32 v[124:125], v[124:125], v[154:155] op_sel_hi:[1,0]
	v_pk_mul_f32 v[122:123], v[122:123], v[154:155] op_sel_hi:[1,0]
	v_pk_mul_f32 v[120:121], v[120:121], v[154:155] op_sel_hi:[1,0]
	v_pk_mul_f32 v[118:119], v[118:119], v[154:155] op_sel_hi:[1,0]
	v_pk_mul_f32 v[116:117], v[116:117], v[154:155] op_sel_hi:[1,0]
	v_pk_mul_f32 v[114:115], v[114:115], v[154:155] op_sel_hi:[1,0]
	v_max_f32_e32 v126, 0, v126
	v_max_f32_e32 v122, 0, v122
	v_max_f32_e32 v127, 0, v127
	v_max_f32_e32 v123, 0, v123
	v_max_f32_e32 v128, 0, v128
	v_max_f32_e32 v124, 0, v124
	v_max_f32_e32 v129, 0, v129
	v_max_f32_e32 v125, 0, v125
	v_max_f32_e32 v118, 0, v118
	v_max_f32_e32 v114, 0, v114
	v_max_f32_e32 v119, 0, v119
	v_max_f32_e32 v115, 0, v115
	v_max_f32_e32 v120, 0, v120
	v_max_f32_e32 v116, 0, v116
	v_max_f32_e32 v121, 0, v121
	v_max_f32_e32 v117, 0, v117
	v_pk_mul_f32 v[126:127], v[126:127], v[126:127]
	v_pk_mul_f32 v[122:123], v[122:123], v[122:123]
	v_pk_mul_f32 v[128:129], v[128:129], v[128:129]
	v_pk_mul_f32 v[124:125], v[124:125], v[124:125]
	v_pk_mul_f32 v[118:119], v[118:119], v[118:119]
	v_pk_mul_f32 v[154:155], v[114:115], v[114:115]
	v_pk_mul_f32 v[120:121], v[120:121], v[120:121]
	v_pk_mul_f32 v[162:163], v[116:117], v[116:117]
	v_cvt_pk_bf16_f32 v114, v126, v127
	v_cvt_pk_bf16_f32 v115, v128, v129
	v_cvt_pk_bf16_f32 v116, v122, v123
	v_cvt_pk_bf16_f32 v117, v124, v125
	v_cvt_pk_bf16_f32 v118, v118, v119
	v_cvt_pk_bf16_f32 v119, v120, v121
	v_cvt_pk_bf16_f32 v120, v154, v155
	v_cvt_pk_bf16_f32 v121, v162, v163
	global_store_dwordx4 v[158:159], v[114:117], off
	global_store_dwordx4 v[158:159], v[118:121], off offset:256
	s_nop 0
	v_or_b32_e32 v116, 32, v148
	v_lshlrev_b64 v[118:119], 14, v[156:157]
	v_lshl_add_u64 v[118:119], s[6:7], 0, v[118:119]
	v_lshl_add_u64 v[118:119], v[118:119], 0, s[18:19]
	v_ashrrev_i32_e32 v117, 31, v116
	v_lshl_add_u64 v[118:119], v[118:119], 0, v[138:139]
	v_lshl_add_u64 v[120:121], v[116:117], 2, s[4:5]
	v_mov_b32_e32 v114, v240
;   DI void operator()(const f32x4 (&acc)[2][2][4][2], const pg8::Unit& u, int wr, int wc, int fr, int fq) const {
;     ...
;           f32x4 v0 = acc[ai][bj][m][0] * rs, v1 = acc[ai][bj][m][1] * rs;
;           if (MODE == EP_IN || MODE == EP_MIX || MODE == EP_DOWN) {
; #pragma unroll
;             for (int j = 0; j < 4; ++j) ssq += v0[j] * v0[j] + v1[j] * v1[j];
;           }
;           if (MODE == EP_UP) {
; #pragma unroll
;             for (int j = 0; j < 4; ++j) { float a = fmaxf(v0[j], 0.f), b = fmaxf(v1[j], 0.f); v0[j] = a * a; v1[j] = b * b; }
;           }
;           bf16_t* dst;
;           const int ct = bj * 128 + cl;
;           if (MODE == EP_IN) {
;             if (pn < 4) dst = (bf16_t*)(ws + OFF_PROJA) + (size_t)grow * 1024 + pn * 256 + ct;
;             else if (pn < 16) dst = (bf16_t*)(ws + OFF_PROJG) + (size_t)grow * 3072 + (pn - 4) * 256 + ct;
;             else dst = (bf16_t*)(ws + OFF_PROJS) + (size_t)grow * 256 + ct;
;           } else if (MODE == EP_Q) {
;             if (pn < 4) dst = (bf16_t*)(dout + DO_Q) + (size_t)grow * 1536 + (pn * 2 + bj) * 192 + cl;
;             else {
;               const int mm = (pn - 4) * 256 + ct, h = mm >> 6, r = mm & 63;
;               dst = (bf16_t*)(dout + DO_Q) + (size_t)grow * 1536 + h * 192 + 128 + r;
;               const int pos = grow < TP ? (grow & 4095) : grow - TP;
;               const f32x4* tb = (const f32x4*)((const f32x2*)(ws + OFF_ROPE) + pos * 32 + (r >> 1));
;               const f32x4 t0 = tb[0], t1 = tb[1];
;               f32x4 o0, o1;
;               o0[0] = v0[0] * t0[0] - v0[1] * t0[1]; o0[1] = v0[1] * t0[0] + v0[0] * t0[1];
;               o0[2] = v0[2] * t0[2] - v0[3] * t0[3]; o0[3] = v0[3] * t0[2] + v0[2] * t0[3];
;               o1[0] = v1[0] * t1[0] - v1[1] * t1[1]; o1[1] = v1[1] * t1[0] + v1[0] * t1[1];
;               o1[2] = v1[2] * t1[2] - v1[3] * t1[3]; o1[3] = v1[3] * t1[2] + v1[2] * t1[3];
;               v0 = o0; v1 = o1;
;             }
;           } else if (MODE == EP_KV) {
;             dst = (bf16_t*)(ws + OFF_XB) + (size_t)grow * 2048 + pn * 256 + ct;
;           } else if (MODE == EP_MIX) {
;             dst = (bf16_t*)(ws + OFF_MIX) + (size_t)grow * 2048 + pn * 256 + ct;
;           } else if (MODE == EP_UP) {
;             dst = (bf16_t*)(ws + OFF_U) + (size_t)row * 8192 + pn * 256 + ct;
;           } else {
	v_pk_mul_f32 v[112:113], v[112:113], v[114:115] op_sel_hi:[1,0]
	v_pk_mul_f32 v[110:111], v[110:111], v[114:115] op_sel_hi:[1,0]
	v_pk_mul_f32 v[108:109], v[108:109], v[114:115] op_sel_hi:[1,0]
	v_pk_mul_f32 v[106:107], v[106:107], v[114:115] op_sel_hi:[1,0]
	v_pk_mul_f32 v[104:105], v[104:105], v[114:115] op_sel_hi:[1,0]
	v_pk_mul_f32 v[102:103], v[102:103], v[114:115] op_sel_hi:[1,0]
	v_pk_mul_f32 v[100:101], v[100:101], v[114:115] op_sel_hi:[1,0]
	v_pk_mul_f32 v[98:99], v[98:99], v[114:115] op_sel_hi:[1,0]
	v_max_f32_e32 v110, 0, v110
	v_max_f32_e32 v106, 0, v106
	v_max_f32_e32 v111, 0, v111
	v_max_f32_e32 v107, 0, v107
	v_max_f32_e32 v112, 0, v112
	v_max_f32_e32 v108, 0, v108
	v_max_f32_e32 v113, 0, v113
	v_max_f32_e32 v109, 0, v109
	v_max_f32_e32 v102, 0, v102
	v_max_f32_e32 v98, 0, v98
	v_max_f32_e32 v103, 0, v103
	v_max_f32_e32 v99, 0, v99
	v_max_f32_e32 v104, 0, v104
	v_max_f32_e32 v100, 0, v100
	v_max_f32_e32 v105, 0, v105
	v_max_f32_e32 v101, 0, v101
	v_pk_mul_f32 v[110:111], v[110:111], v[110:111]
	v_pk_mul_f32 v[106:107], v[106:107], v[106:107]
	v_pk_mul_f32 v[112:113], v[112:113], v[112:113]
	v_pk_mul_f32 v[108:109], v[108:109], v[108:109]
	v_pk_mul_f32 v[102:103], v[102:103], v[102:103]
	v_pk_mul_f32 v[114:115], v[98:99], v[98:99]
	v_pk_mul_f32 v[104:105], v[104:105], v[104:105]
	v_pk_mul_f32 v[122:123], v[100:101], v[100:101]
	v_cvt_pk_bf16_f32 v98, v110, v111
	v_cvt_pk_bf16_f32 v99, v112, v113
	v_cvt_pk_bf16_f32 v100, v106, v107
	v_cvt_pk_bf16_f32 v101, v108, v109
	v_cvt_pk_bf16_f32 v102, v102, v103
	v_cvt_pk_bf16_f32 v103, v104, v105
	v_cvt_pk_bf16_f32 v104, v114, v115
	v_cvt_pk_bf16_f32 v105, v122, v123
	global_store_dwordx4 v[118:119], v[98:101], off
	global_store_dwordx4 v[118:119], v[102:105], off offset:256
	s_nop 0
	v_or_b32_e32 v100, 48, v148
	v_lshlrev_b64 v[102:103], 14, v[116:117]
	v_lshl_add_u64 v[102:103], s[6:7], 0, v[102:103]
	v_lshl_add_u64 v[102:103], v[102:103], 0, s[18:19]
	v_ashrrev_i32_e32 v101, 31, v100
	v_lshl_add_u64 v[102:103], v[102:103], 0, v[138:139]
	v_lshl_add_u64 v[104:105], v[100:101], 2, s[4:5]
	v_mov_b32_e32 v98, v241
	v_pk_mul_f32 v[96:97], v[96:97], v[98:99] op_sel_hi:[1,0]
	v_pk_mul_f32 v[94:95], v[94:95], v[98:99] op_sel_hi:[1,0]
	v_pk_mul_f32 v[92:93], v[92:93], v[98:99] op_sel_hi:[1,0]
	v_pk_mul_f32 v[90:91], v[90:91], v[98:99] op_sel_hi:[1,0]
	v_pk_mul_f32 v[88:89], v[88:89], v[98:99] op_sel_hi:[1,0]
	v_pk_mul_f32 v[86:87], v[86:87], v[98:99] op_sel_hi:[1,0]
	v_pk_mul_f32 v[84:85], v[84:85], v[98:99] op_sel_hi:[1,0]
	v_pk_mul_f32 v[82:83], v[82:83], v[98:99] op_sel_hi:[1,0]
	v_max_f32_e32 v94, 0, v94
	v_max_f32_e32 v90, 0, v90
	v_max_f32_e32 v95, 0, v95
	v_max_f32_e32 v91, 0, v91
	v_max_f32_e32 v96, 0, v96
	v_max_f32_e32 v92, 0, v92
	v_max_f32_e32 v97, 0, v97
	v_max_f32_e32 v93, 0, v93
	v_max_f32_e32 v86, 0, v86
	v_max_f32_e32 v82, 0, v82
	v_max_f32_e32 v87, 0, v87
	v_max_f32_e32 v83, 0, v83
	v_max_f32_e32 v88, 0, v88
	v_max_f32_e32 v84, 0, v84
	v_max_f32_e32 v89, 0, v89
	v_max_f32_e32 v85, 0, v85
	v_pk_mul_f32 v[94:95], v[94:95], v[94:95]
	v_pk_mul_f32 v[90:91], v[90:91], v[90:91]
	v_pk_mul_f32 v[96:97], v[96:97], v[96:97]
	v_pk_mul_f32 v[92:93], v[92:93], v[92:93]
	v_pk_mul_f32 v[86:87], v[86:87], v[86:87]
	v_pk_mul_f32 v[98:99], v[82:83], v[82:83]
	v_pk_mul_f32 v[88:89], v[88:89], v[88:89]
	v_pk_mul_f32 v[106:107], v[84:85], v[84:85]
	v_cvt_pk_bf16_f32 v82, v94, v95
	v_cvt_pk_bf16_f32 v83, v96, v97
	v_cvt_pk_bf16_f32 v84, v90, v91
	v_cvt_pk_bf16_f32 v85, v92, v93
	v_cvt_pk_bf16_f32 v86, v86, v87
	v_cvt_pk_bf16_f32 v87, v88, v89
	v_cvt_pk_bf16_f32 v88, v98, v99
	v_cvt_pk_bf16_f32 v89, v106, v107
	global_store_dwordx4 v[102:103], v[82:85], off
	global_store_dwordx4 v[102:103], v[86:89], off offset:256
	s_nop 0
	v_add_u32_e32 v84, 0x80, v148
	v_lshlrev_b64 v[86:87], 14, v[100:101]
	v_lshl_add_u64 v[86:87], s[6:7], 0, v[86:87]
	v_lshl_add_u64 v[86:87], v[86:87], 0, s[18:19]
	v_ashrrev_i32_e32 v85, 31, v84
	v_lshl_add_u64 v[86:87], v[86:87], 0, v[138:139]
	v_lshl_add_u64 v[88:89], v[84:85], 2, s[4:5]
	v_mov_b32_e32 v82, v242
	v_pk_mul_f32 v[80:81], v[80:81], v[82:83] op_sel_hi:[1,0]
	v_pk_mul_f32 v[78:79], v[78:79], v[82:83] op_sel_hi:[1,0]
	v_pk_mul_f32 v[76:77], v[76:77], v[82:83] op_sel_hi:[1,0]
	v_pk_mul_f32 v[74:75], v[74:75], v[82:83] op_sel_hi:[1,0]
	v_pk_mul_f32 v[72:73], v[72:73], v[82:83] op_sel_hi:[1,0]
	v_pk_mul_f32 v[70:71], v[70:71], v[82:83] op_sel_hi:[1,0]
	v_pk_mul_f32 v[68:69], v[68:69], v[82:83] op_sel_hi:[1,0]
	v_pk_mul_f32 v[66:67], v[66:67], v[82:83] op_sel_hi:[1,0]
	v_max_f32_e32 v78, 0, v78
	v_max_f32_e32 v74, 0, v74
	v_max_f32_e32 v79, 0, v79
	v_max_f32_e32 v75, 0, v75
	v_max_f32_e32 v80, 0, v80
	v_max_f32_e32 v76, 0, v76
	v_max_f32_e32 v81, 0, v81
	v_max_f32_e32 v77, 0, v77
	v_max_f32_e32 v70, 0, v70
	v_max_f32_e32 v66, 0, v66
	v_max_f32_e32 v71, 0, v71
	v_max_f32_e32 v67, 0, v67
	v_max_f32_e32 v72, 0, v72
	v_max_f32_e32 v68, 0, v68
	v_max_f32_e32 v73, 0, v73
	v_max_f32_e32 v69, 0, v69
	v_pk_mul_f32 v[78:79], v[78:79], v[78:79]
	v_pk_mul_f32 v[74:75], v[74:75], v[74:75]
	v_pk_mul_f32 v[80:81], v[80:81], v[80:81]
	v_pk_mul_f32 v[76:77], v[76:77], v[76:77]
	v_pk_mul_f32 v[70:71], v[70:71], v[70:71]
	v_pk_mul_f32 v[82:83], v[66:67], v[66:67]
	v_pk_mul_f32 v[72:73], v[72:73], v[72:73]
	v_pk_mul_f32 v[90:91], v[68:69], v[68:69]
	v_cvt_pk_bf16_f32 v66, v78, v79
	v_cvt_pk_bf16_f32 v67, v80, v81
	v_cvt_pk_bf16_f32 v68, v74, v75
	v_cvt_pk_bf16_f32 v69, v76, v77
	v_cvt_pk_bf16_f32 v70, v70, v71
	v_cvt_pk_bf16_f32 v71, v72, v73
	v_cvt_pk_bf16_f32 v72, v82, v83
	v_cvt_pk_bf16_f32 v73, v90, v91
	global_store_dwordx4 v[86:87], v[66:69], off
;   DI void operator()(const f32x4 (&acc)[2][2][4][2], const pg8::Unit& u, int wr, int wc, int fr, int fq) const {
;     ...
;           f32x4 v0 = acc[ai][bj][m][0] * rs, v1 = acc[ai][bj][m][1] * rs;
;           if (MODE == EP_IN || MODE == EP_MIX || MODE == EP_DOWN) {
; #pragma unroll
;             for (int j = 0; j < 4; ++j) ssq += v0[j] * v0[j] + v1[j] * v1[j];
;           }
;           if (MODE == EP_UP) {
; #pragma unroll
;             for (int j = 0; j < 4; ++j) { float a = fmaxf(v0[j], 0.f), b = fmaxf(v1[j], 0.f); v0[j] = a * a; v1[j] = b * b; }
;           }
;           bf16_t* dst;
;           const int ct = bj * 128 + cl;
;           if (MODE == EP_IN) {
;             if (pn < 4) dst = (bf16_t*)(ws + OFF_PROJA) + (size_t)grow * 1024 + pn * 256 + ct;
;             else if (pn < 16) dst = (bf16_t*)(ws + OFF_PROJG) + (size_t)grow * 3072 + (pn - 4) * 256 + ct;
;             else dst = (bf16_t*)(ws + OFF_PROJS) + (size_t)grow * 256 + ct;
;           } else if (MODE == EP_Q) {
;             if (pn < 4) dst = (bf16_t*)(dout + DO_Q) + (size_t)grow * 1536 + (pn * 2 + bj) * 192 + cl;
;             else {
;               const int mm = (pn - 4) * 256 + ct, h = mm >> 6, r = mm & 63;
;               dst = (bf16_t*)(dout + DO_Q) + (size_t)grow * 1536 + h * 192 + 128 + r;
;               const int pos = grow < TP ? (grow & 4095) : grow - TP;
;               const f32x4* tb = (const f32x4*)((const f32x2*)(ws + OFF_ROPE) + pos * 32 + (r >> 1));
;               const f32x4 t0 = tb[0], t1 = tb[1];
;               f32x4 o0, o1;
;               o0[0] = v0[0] * t0[0] - v0[1] * t0[1]; o0[1] = v0[1] * t0[0] + v0[0] * t0[1];
;               o0[2] = v0[2] * t0[2] - v0[3] * t0[3]; o0[3] = v0[3] * t0[2] + v0[2] * t0[3];
;               o1[0] = v1[0] * t1[0] - v1[1] * t1[1]; o1[1] = v1[1] * t1[0] + v1[0] * t1[1];
;               o1[2] = v1[2] * t1[2] - v1[3] * t1[3]; o1[3] = v1[3] * t1[2] + v1[2] * t1[3];
;               v0 = o0; v1 = o1;
;             }
;           } else if (MODE == EP_KV) {
;             dst = (bf16_t*)(ws + OFF_XB) + (size_t)grow * 2048 + pn * 256 + ct;
;           } else if (MODE == EP_MIX) {
;             dst = (bf16_t*)(ws + OFF_MIX) + (size_t)grow * 2048 + pn * 256 + ct;
;           } else if (MODE == EP_UP) {
;             dst = (bf16_t*)(ws + OFF_U) + (size_t)row * 8192 + pn * 256 + ct;
;           } else {
	global_store_dwordx4 v[86:87], v[70:73], off offset:256
	s_nop 0
	v_add_u32_e32 v68, 0x90, v148
	v_lshlrev_b64 v[70:71], 14, v[84:85]
	v_lshl_add_u64 v[70:71], s[6:7], 0, v[70:71]
	v_lshl_add_u64 v[70:71], v[70:71], 0, s[18:19]
	v_ashrrev_i32_e32 v69, 31, v68
	v_lshl_add_u64 v[70:71], v[70:71], 0, v[138:139]
	v_lshl_add_u64 v[72:73], v[68:69], 2, s[4:5]
	v_mov_b32_e32 v66, v243
	v_pk_mul_f32 v[64:65], v[64:65], v[66:67] op_sel_hi:[1,0]
	v_pk_mul_f32 v[62:63], v[62:63], v[66:67] op_sel_hi:[1,0]
	v_pk_mul_f32 v[60:61], v[60:61], v[66:67] op_sel_hi:[1,0]
	v_pk_mul_f32 v[58:59], v[58:59], v[66:67] op_sel_hi:[1,0]
	v_pk_mul_f32 v[56:57], v[56:57], v[66:67] op_sel_hi:[1,0]
	v_pk_mul_f32 v[54:55], v[54:55], v[66:67] op_sel_hi:[1,0]
	v_pk_mul_f32 v[52:53], v[52:53], v[66:67] op_sel_hi:[1,0]
	v_pk_mul_f32 v[50:51], v[50:51], v[66:67] op_sel_hi:[1,0]
	v_max_f32_e32 v62, 0, v62
	v_max_f32_e32 v58, 0, v58
	v_max_f32_e32 v63, 0, v63
	v_max_f32_e32 v59, 0, v59
	v_max_f32_e32 v64, 0, v64
	v_max_f32_e32 v60, 0, v60
	v_max_f32_e32 v65, 0, v65
	v_max_f32_e32 v61, 0, v61
	v_max_f32_e32 v54, 0, v54
	v_max_f32_e32 v50, 0, v50
	v_max_f32_e32 v55, 0, v55
	v_max_f32_e32 v51, 0, v51
	v_max_f32_e32 v56, 0, v56
	v_max_f32_e32 v52, 0, v52
	v_max_f32_e32 v57, 0, v57
	v_max_f32_e32 v53, 0, v53
	v_pk_mul_f32 v[62:63], v[62:63], v[62:63]
	v_pk_mul_f32 v[58:59], v[58:59], v[58:59]
	v_pk_mul_f32 v[64:65], v[64:65], v[64:65]
	v_pk_mul_f32 v[60:61], v[60:61], v[60:61]
	v_pk_mul_f32 v[54:55], v[54:55], v[54:55]
	v_pk_mul_f32 v[66:67], v[50:51], v[50:51]
	v_pk_mul_f32 v[56:57], v[56:57], v[56:57]
	v_pk_mul_f32 v[74:75], v[52:53], v[52:53]
	v_cvt_pk_bf16_f32 v50, v62, v63
	v_cvt_pk_bf16_f32 v51, v64, v65
	v_cvt_pk_bf16_f32 v52, v58, v59
	v_cvt_pk_bf16_f32 v53, v60, v61
	v_cvt_pk_bf16_f32 v54, v54, v55
	v_cvt_pk_bf16_f32 v55, v56, v57
	v_cvt_pk_bf16_f32 v56, v66, v67
	v_cvt_pk_bf16_f32 v57, v74, v75
	global_store_dwordx4 v[70:71], v[50:53], off
	global_store_dwordx4 v[70:71], v[54:57], off offset:256
	s_nop 0
	v_add_u32_e32 v52, 0xa0, v148
	v_lshlrev_b64 v[54:55], 14, v[68:69]
	v_lshl_add_u64 v[54:55], s[6:7], 0, v[54:55]
	v_lshl_add_u64 v[54:55], v[54:55], 0, s[18:19]
	v_ashrrev_i32_e32 v53, 31, v52
	v_lshl_add_u64 v[54:55], v[54:55], 0, v[138:139]
	v_lshl_add_u64 v[56:57], v[52:53], 2, s[4:5]
	v_mov_b32_e32 v50, v244
	v_pk_mul_f32 v[48:49], v[48:49], v[50:51] op_sel_hi:[1,0]
	v_pk_mul_f32 v[46:47], v[46:47], v[50:51] op_sel_hi:[1,0]
	v_pk_mul_f32 v[44:45], v[44:45], v[50:51] op_sel_hi:[1,0]
	v_pk_mul_f32 v[42:43], v[42:43], v[50:51] op_sel_hi:[1,0]
	v_pk_mul_f32 v[40:41], v[40:41], v[50:51] op_sel_hi:[1,0]
	v_pk_mul_f32 v[38:39], v[38:39], v[50:51] op_sel_hi:[1,0]
	v_pk_mul_f32 v[36:37], v[36:37], v[50:51] op_sel_hi:[1,0]
	v_pk_mul_f32 v[34:35], v[34:35], v[50:51] op_sel_hi:[1,0]
	v_max_f32_e32 v46, 0, v46
	v_max_f32_e32 v42, 0, v42
	v_max_f32_e32 v47, 0, v47
	v_max_f32_e32 v43, 0, v43
	v_max_f32_e32 v48, 0, v48
	v_max_f32_e32 v44, 0, v44
	v_max_f32_e32 v49, 0, v49
	v_max_f32_e32 v45, 0, v45
	v_max_f32_e32 v38, 0, v38
	v_max_f32_e32 v34, 0, v34
	v_max_f32_e32 v39, 0, v39
	v_max_f32_e32 v35, 0, v35
	v_max_f32_e32 v40, 0, v40
	v_max_f32_e32 v36, 0, v36
	v_max_f32_e32 v41, 0, v41
	v_max_f32_e32 v37, 0, v37
	v_pk_mul_f32 v[46:47], v[46:47], v[46:47]
	v_pk_mul_f32 v[42:43], v[42:43], v[42:43]
	v_pk_mul_f32 v[48:49], v[48:49], v[48:49]
	v_pk_mul_f32 v[44:45], v[44:45], v[44:45]
	v_pk_mul_f32 v[38:39], v[38:39], v[38:39]
	v_pk_mul_f32 v[50:51], v[34:35], v[34:35]
	v_pk_mul_f32 v[40:41], v[40:41], v[40:41]
	v_pk_mul_f32 v[58:59], v[36:37], v[36:37]
	v_cvt_pk_bf16_f32 v34, v46, v47
	v_cvt_pk_bf16_f32 v35, v48, v49
	v_cvt_pk_bf16_f32 v36, v42, v43
	v_cvt_pk_bf16_f32 v37, v44, v45
	v_cvt_pk_bf16_f32 v38, v38, v39
	v_cvt_pk_bf16_f32 v39, v40, v41
	v_cvt_pk_bf16_f32 v40, v50, v51
	v_cvt_pk_bf16_f32 v41, v58, v59
	global_store_dwordx4 v[54:55], v[34:37], off
;   DI void operator()(const f32x4 (&acc)[2][2][4][2], const pg8::Unit& u, int wr, int wc, int fr, int fq) const {
;     ...
;           f32x4 v0 = acc[ai][bj][m][0] * rs, v1 = acc[ai][bj][m][1] * rs;
;           if (MODE == EP_IN || MODE == EP_MIX || MODE == EP_DOWN) {
; #pragma unroll
;             for (int j = 0; j < 4; ++j) ssq += v0[j] * v0[j] + v1[j] * v1[j];
;           }
;           if (MODE == EP_UP) {
; #pragma unroll
;             for (int j = 0; j < 4; ++j) { float a = fmaxf(v0[j], 0.f), b = fmaxf(v1[j], 0.f); v0[j] = a * a; v1[j] = b * b; }
;           }
;           bf16_t* dst;
;           const int ct = bj * 128 + cl;
;           if (MODE == EP_IN) {
;             if (pn < 4) dst = (bf16_t*)(ws + OFF_PROJA) + (size_t)grow * 1024 + pn * 256 + ct;
;             else if (pn < 16) dst = (bf16_t*)(ws + OFF_PROJG) + (size_t)grow * 3072 + (pn - 4) * 256 + ct;
;             else dst = (bf16_t*)(ws + OFF_PROJS) + (size_t)grow * 256 + ct;
;           } else if (MODE == EP_Q) {
;             if (pn < 4) dst = (bf16_t*)(dout + DO_Q) + (size_t)grow * 1536 + (pn * 2 + bj) * 192 + cl;
;             else {
;               const int mm = (pn - 4) * 256 + ct, h = mm >> 6, r = mm & 63;
;               dst = (bf16_t*)(dout + DO_Q) + (size_t)grow * 1536 + h * 192 + 128 + r;
;               const int pos = grow < TP ? (grow & 4095) : grow - TP;
;               const f32x4* tb = (const f32x4*)((const f32x2*)(ws + OFF_ROPE) + pos * 32 + (r >> 1));
;               const f32x4 t0 = tb[0], t1 = tb[1];
;               f32x4 o0, o1;
;               o0[0] = v0[0] * t0[0] - v0[1] * t0[1]; o0[1] = v0[1] * t0[0] + v0[0] * t0[1];
;               o0[2] = v0[2] * t0[2] - v0[3] * t0[3]; o0[3] = v0[3] * t0[2] + v0[2] * t0[3];
;               o1[0] = v1[0] * t1[0] - v1[1] * t1[1]; o1[1] = v1[1] * t1[0] + v1[0] * t1[1];
;               o1[2] = v1[2] * t1[2] - v1[3] * t1[3]; o1[3] = v1[3] * t1[2] + v1[2] * t1[3];
;               v0 = o0; v1 = o1;
;             }
;           } else if (MODE == EP_KV) {
;             dst = (bf16_t*)(ws + OFF_XB) + (size_t)grow * 2048 + pn * 256 + ct;
;           } else if (MODE == EP_MIX) {
;             dst = (bf16_t*)(ws + OFF_MIX) + (size_t)grow * 2048 + pn * 256 + ct;
;           } else if (MODE == EP_UP) {
;             dst = (bf16_t*)(ws + OFF_U) + (size_t)row * 8192 + pn * 256 + ct;
;           } else {
	global_store_dwordx4 v[54:55], v[38:41], off offset:256
	s_nop 0
	v_add_u32_e32 v36, 0xb0, v148
	v_lshlrev_b64 v[38:39], 14, v[52:53]
	v_lshl_add_u64 v[38:39], s[6:7], 0, v[38:39]
	v_lshl_add_u64 v[38:39], v[38:39], 0, s[18:19]
	v_ashrrev_i32_e32 v37, 31, v36
	v_lshl_add_u64 v[38:39], v[38:39], 0, v[138:139]
	v_lshl_add_u64 v[40:41], v[36:37], 2, s[4:5]
	v_mov_b32_e32 v34, v245
	v_pk_mul_f32 v[32:33], v[32:33], v[34:35] op_sel_hi:[1,0]
	v_pk_mul_f32 v[30:31], v[30:31], v[34:35] op_sel_hi:[1,0]
	v_pk_mul_f32 v[28:29], v[28:29], v[34:35] op_sel_hi:[1,0]
	v_pk_mul_f32 v[26:27], v[26:27], v[34:35] op_sel_hi:[1,0]
	v_pk_mul_f32 v[24:25], v[24:25], v[34:35] op_sel_hi:[1,0]
	v_pk_mul_f32 v[22:23], v[22:23], v[34:35] op_sel_hi:[1,0]
	v_pk_mul_f32 v[20:21], v[20:21], v[34:35] op_sel_hi:[1,0]
	v_pk_mul_f32 v[18:19], v[18:19], v[34:35] op_sel_hi:[1,0]
	v_max_f32_e32 v30, 0, v30
	v_max_f32_e32 v26, 0, v26
	v_max_f32_e32 v31, 0, v31
	v_max_f32_e32 v27, 0, v27
	v_max_f32_e32 v32, 0, v32
	v_max_f32_e32 v28, 0, v28
	v_max_f32_e32 v33, 0, v33
	v_max_f32_e32 v29, 0, v29
	v_max_f32_e32 v22, 0, v22
	v_max_f32_e32 v18, 0, v18
	v_max_f32_e32 v23, 0, v23
	v_max_f32_e32 v19, 0, v19
	v_max_f32_e32 v24, 0, v24
	v_max_f32_e32 v20, 0, v20
	v_max_f32_e32 v25, 0, v25
	v_max_f32_e32 v21, 0, v21
	v_pk_mul_f32 v[30:31], v[30:31], v[30:31]
	v_pk_mul_f32 v[26:27], v[26:27], v[26:27]
	v_pk_mul_f32 v[32:33], v[32:33], v[32:33]
	v_pk_mul_f32 v[28:29], v[28:29], v[28:29]
	v_pk_mul_f32 v[22:23], v[22:23], v[22:23]
	v_pk_mul_f32 v[34:35], v[18:19], v[18:19]
	v_pk_mul_f32 v[24:25], v[24:25], v[24:25]
	v_pk_mul_f32 v[42:43], v[20:21], v[20:21]
	v_cvt_pk_bf16_f32 v18, v30, v31
	v_cvt_pk_bf16_f32 v19, v32, v33
	v_cvt_pk_bf16_f32 v20, v26, v27
	v_cvt_pk_bf16_f32 v21, v28, v29
	v_cvt_pk_bf16_f32 v22, v22, v23
	v_cvt_pk_bf16_f32 v23, v24, v25
	v_cvt_pk_bf16_f32 v24, v34, v35
	v_cvt_pk_bf16_f32 v25, v42, v43
	global_store_dwordx4 v[38:39], v[18:21], off
	global_store_dwordx4 v[38:39], v[22:25], off offset:256
	s_nop 0
	v_lshlrev_b64 v[20:21], 14, v[36:37]
	v_lshl_add_u64 v[20:21], s[6:7], 0, v[20:21]
	v_lshl_add_u64 v[20:21], v[20:21], 0, s[18:19]
	v_lshl_add_u64 v[20:21], v[20:21], 0, v[138:139]
	v_mov_b32_e32 v18, v246
	v_pk_mul_f32 v[16:17], v[16:17], v[18:19] op_sel_hi:[1,0]
	v_pk_mul_f32 v[14:15], v[14:15], v[18:19] op_sel_hi:[1,0]
	v_pk_mul_f32 v[12:13], v[12:13], v[18:19] op_sel_hi:[1,0]
	v_pk_mul_f32 v[10:11], v[10:11], v[18:19] op_sel_hi:[1,0]
	v_pk_mul_f32 v[8:9], v[8:9], v[18:19] op_sel_hi:[1,0]
	v_pk_mul_f32 v[6:7], v[6:7], v[18:19] op_sel_hi:[1,0]
	v_pk_mul_f32 v[4:5], v[4:5], v[18:19] op_sel_hi:[1,0]
	v_pk_mul_f32 v[2:3], v[2:3], v[18:19] op_sel_hi:[1,0]
	v_max_f32_e32 v14, 0, v14
	v_max_f32_e32 v10, 0, v10
	v_max_f32_e32 v15, 0, v15
	v_max_f32_e32 v11, 0, v11
	v_max_f32_e32 v16, 0, v16
	v_max_f32_e32 v12, 0, v12
	v_max_f32_e32 v17, 0, v17
	v_max_f32_e32 v13, 0, v13
	v_max_f32_e32 v6, 0, v6
	v_max_f32_e32 v2, 0, v2
	v_max_f32_e32 v7, 0, v7
	v_max_f32_e32 v3, 0, v3
	v_max_f32_e32 v8, 0, v8
	v_max_f32_e32 v4, 0, v4
	v_max_f32_e32 v9, 0, v9
	v_max_f32_e32 v5, 0, v5
	v_pk_mul_f32 v[14:15], v[14:15], v[14:15]
	v_pk_mul_f32 v[10:11], v[10:11], v[10:11]
	v_pk_mul_f32 v[16:17], v[16:17], v[16:17]
	v_pk_mul_f32 v[12:13], v[12:13], v[12:13]
	v_pk_mul_f32 v[6:7], v[6:7], v[6:7]
	v_pk_mul_f32 v[18:19], v[2:3], v[2:3]
	v_pk_mul_f32 v[8:9], v[8:9], v[8:9]
	v_pk_mul_f32 v[22:23], v[4:5], v[4:5]
	v_cvt_pk_bf16_f32 v2, v14, v15
	v_cvt_pk_bf16_f32 v3, v16, v17
	v_cvt_pk_bf16_f32 v4, v10, v11
	v_cvt_pk_bf16_f32 v5, v12, v13
	v_cvt_pk_bf16_f32 v6, v6, v7
	v_cvt_pk_bf16_f32 v7, v8, v9
	v_cvt_pk_bf16_f32 v8, v18, v19
	v_cvt_pk_bf16_f32 v9, v22, v23
	global_store_dwordx4 v[20:21], v[2:5], off
	global_store_dwordx4 v[20:21], v[6:9], off offset:256
	s_cbranch_vccz .LBB0_914
	s_waitcnt vmcnt(0)
	s_cmpk_gt_u32 s24, 0xff
	s_cbranch_scc1 .LBB0_925
	s_barrier

;   DI bool next(int i, Unit& u) const {
;     const long L = (long)i * G + c; if (L >= nwg) return false;
;     int wgid = (int)L; { const int q = nwg / NXCD, r = nwg % NXCD, xcd = wgid % NXCD, off = wgid / NXCD; wgid = (xcd < r ? xcd * (q + 1) : r * (q + 1) + (xcd - r) * q) + off; }
;     const int nig = wgm * nN, gid = wgid / nig, fm = gid * wgm, gsz = (nM - fm) < wgm ? (nM - fm) : wgm;
;     u.pm = fm + ((wgid % nig) % gsz); u.pn = (wgid % nig) / gsz; return true;
;   }
;   DI void operator()(const f32x4 (&acc)[2][2][4][2], const pg8::Unit& u, int wr, int wc, int fr, int fq) const {
;     ...
;         const int row = u.pm * 256 + ai * 128 + wr * 64 + m * 16 + fr;
;         const int grow = rowbase + row;
;         float rs = 1.f;
;         if (MODE == EP_IN) rs = ((const float*)(ws + OFF_RS0))[grow];
;         if (MODE == EP_UP) rs = ((const float*)(ws + OFF_RS2))[grow];
.LBB0_1008:
	v_lshl_add_u32 v248, s16, 8, v1
	v_add_u32_e32 v248, 0x4000, v248
	v_ashrrev_i32_e32 v249, 31, v248
	v_lshl_add_u64 v[248:249], v[248:249], 2, s[4:5]
	global_load_dword v247, v[248:249], off
	global_load_dword v240, v[248:249], off offset:64
	global_load_dword v241, v[248:249], off offset:128
	global_load_dword v242, v[248:249], off offset:192
	global_load_dword v243, v[248:249], off offset:512
	global_load_dword v244, v[248:249], off offset:576
	global_load_dword v245, v[248:249], off offset:640
	global_load_dword v246, v[248:249], off offset:704
	s_add_i32 s35, s35, 1
	s_mul_i32 s0, s35, s38
	s_mul_hi_u32 s1, s35, s68
	s_add_i32 s1, s1, s0
	s_mul_i32 s0, s35, s68
	s_add_u32 s12, s0, s60
	s_addc_u32 s13, s1, s25
	v_cmp_gt_i64_e64 s[0:1], s[12:13], v[146:147]
	s_and_b64 vcc, exec, s[0:1]
	s_cbranch_vccnz .LBB0_1014
	s_ashr_i32 s8, s12, 31
	s_lshr_b32 s8, s8, 29
	s_add_i32 s10, s12, s8
	s_and_b32 s8, s10, -8
	s_sub_i32 s11, s12, s8
	s_cmp_gt_i32 s11, -1
	s_mov_b64 s[8:9], -1
	s_cbranch_scc0 .LBB0_1011
	s_lshl_b32 s14, s11, 8
	s_mov_b64 s[8:9], 0

; #define PG8_STAGE(bufoff, gbase, voff) do { _Pragma("unroll") for (int _i = 0; _i < 2; ++_i) \
;     __builtin_amdgcn_global_load_lds((const unsigned*)((const char*)(gbase) + (voff)[_i]), (LAS unsigned*)(lds + (bufoff) + ldsw + _i * 8192), 16, 0, 0); } while (0)
; #define PG8_LDA(dst, b, h) do { _Pragma("unroll") for (int m = 0; m < 4; ++m) _Pragma("unroll") for (int k = 0; k < 2; ++k) dst[m][k] = *(const LAS bf16x8*)(lds + PG8_SA(b, h) + aoff + m * 2048 + k * 1024); } while (0)
; #define PG8_LDB(dst, b, h) do { _Pragma("unroll") for (int n = 0; n < 2; ++n) _Pragma("unroll") for (int k = 0; k < 2; ++k) dst[n][k] = *(const LAS bf16x8*)(lds + PG8_SB(b, h) + boff + n * 2048 + k * 1024); } while (0)
; #define PG8_MMA(ai, bj, At, Bt) do { __builtin_amdgcn_s_setprio(1); _Pragma("unroll") for (int m = 0; m < 4; ++m) _Pragma("unroll") for (int n = 0; n < 2; ++n) _Pragma("unroll") for (int k = 0; k < 2; ++k) \
;     acc[ai][bj][m][n] = __builtin_amdgcn_mfma_f32_16x16x32_bf16(Bt[n][k], At[m][k], acc[ai][bj][m][n], 0, 0, 0); __builtin_amdgcn_s_setprio(0); } while (0)
; #define PG8_WAIT_L(n) asm volatile("s_waitcnt lgkmcnt(" #n ")" ::: "memory")
; #define PG8_BAR __builtin_amdgcn_s_barrier()
; #define PG8_SCHED __builtin_amdgcn_sched_barrier(0)
; template <class Epi>
; DI void gemm_phase(LAS unsigned char* lds, const Gemm g, const StaticOrder& S, const Epi& E) {
;     ...
;       PG8_LDB(B0, 0, 0); PG8_SCHED; PG8_LDA(At, 0, 0); PG8_STAGE(PG8_SA(1, 1), a1 + hstepA, voffA);
;       PG8_WAIT_L(8); PG8_BAR; PG8_WAIT_L(0); PG8_MMA(0, 0, At, B0); PG8_BAR; PG8_SCHED;
;       PG8_LDB(B1, 0, 1); PG8_STAGE(PG8_SB(0, 0), b2, voffB);
;       PG8_BAR; PG8_WAIT_L(0); PG8_MMA(0, 1, At, B1); PG8_BAR;
;       PG8_LDA(At, 0, 1); PG8_STAGE(PG8_SA(0, 0), a2, voffA);
;       PG8_BAR; PG8_WAIT_L(0); PG8_MMA(1, 0, At, B0); PG8_BAR; PG8_SCHED;
.LBB0_1015:
	ds_read_b128 v[148:151], v153
	ds_read_b128 v[156:159], v153 offset:1024
	ds_read_b128 v[160:163], v153 offset:2048
	ds_read_b128 v[164:167], v153 offset:3072
	s_add_u32 s20, s18, 0xfff80080
	s_addc_u32 s21, s19, -1
	s_cmp_eq_u32 s46, 28
	s_cselect_b32 s23, s11, s21
	s_cselect_b32 s22, s42, s20
	s_cselect_b32 s21, s9, s45
	s_cselect_b32 s20, s43, s44
	v_lshl_add_u64 v[200:201], s[18:19], 0, v[140:141]
	s_add_i32 m0, s17, 0xc000
	ds_read_b128 v[168:171], v154
	ds_read_b128 v[172:175], v154 offset:1024
	ds_read_b128 v[176:179], v154 offset:2048
	ds_read_b128 v[180:183], v154 offset:3072
	ds_read_b128 v[184:187], v154 offset:4096
	ds_read_b128 v[188:191], v154 offset:5120
	ds_read_b128 v[192:195], v154 offset:6144
	ds_read_b128 v[196:199], v154 offset:7168
	global_load_lds_dwordx4 v[200:201], off
	v_lshl_add_u64 v[200:201], s[18:19], 0, v[142:143]
	s_add_i32 m0, s17, 0xe000
	s_nop 0
	global_load_lds_dwordx4 v[200:201], off
	s_waitcnt lgkmcnt(8)
	s_barrier
	s_waitcnt lgkmcnt(0)
	s_setprio 1
	s_waitcnt lgkmcnt(0)
	v_mfma_f32_16x16x32_bf16 v[126:129], v[148:151], v[168:171], v[126:129]
	v_mfma_f32_16x16x32_bf16 v[122:125], v[160:163], v[168:171], v[122:125]
	v_mfma_f32_16x16x32_bf16 v[110:113], v[148:151], v[176:179], v[110:113]
	v_mfma_f32_16x16x32_bf16 v[106:109], v[160:163], v[176:179], v[106:109]
	v_mfma_f32_16x16x32_bf16 v[94:97], v[148:151], v[184:187], v[94:97]
	v_mfma_f32_16x16x32_bf16 v[90:93], v[160:163], v[184:187], v[90:93]
	v_mfma_f32_16x16x32_bf16 v[78:81], v[148:151], v[192:195], v[78:81]
	v_mfma_f32_16x16x32_bf16 v[74:77], v[160:163], v[192:195], v[74:77]
	v_mfma_f32_16x16x32_bf16 v[126:129], v[156:159], v[172:175], v[126:129]
	v_mfma_f32_16x16x32_bf16 v[122:125], v[164:167], v[172:175], v[122:125]
	v_mfma_f32_16x16x32_bf16 v[110:113], v[156:159], v[180:183], v[110:113]
	v_mfma_f32_16x16x32_bf16 v[106:109], v[164:167], v[180:183], v[106:109]
	v_mfma_f32_16x16x32_bf16 v[94:97], v[156:159], v[188:191], v[94:97]
	v_mfma_f32_16x16x32_bf16 v[90:93], v[164:167], v[188:191], v[90:93]
	v_mfma_f32_16x16x32_bf16 v[78:81], v[156:159], v[196:199], v[78:81]
	v_mfma_f32_16x16x32_bf16 v[74:77], v[164:167], v[196:199], v[74:77]
	s_setprio 0
	s_barrier
	s_add_i32 s47, s39, s30
	v_lshl_add_u64 v[216:217], s[20:21], 0, v[132:133]
	s_mov_b32 m0, s47
	ds_read_b128 v[200:203], v155
	ds_read_b128 v[204:207], v155 offset:1024
	ds_read_b128 v[208:211], v155 offset:2048
	ds_read_b128 v[212:215], v155 offset:3072
	global_load_lds_dwordx4 v[216:217], off
	v_lshl_add_u64 v[218:219], s[20:21], 0, v[136:137]
	s_add_i32 m0, s47, 0x2000
	s_nop 0
	global_load_lds_dwordx4 v[218:219], off
	s_barrier
	s_waitcnt lgkmcnt(0)
	s_setprio 1
	s_waitcnt lgkmcnt(0)
	v_mfma_f32_16x16x32_bf16 v[118:121], v[200:203], v[168:171], v[118:121]
	v_mfma_f32_16x16x32_bf16 v[114:117], v[208:211], v[168:171], v[114:117]
	v_mfma_f32_16x16x32_bf16 v[102:105], v[200:203], v[176:179], v[102:105]
	v_mfma_f32_16x16x32_bf16 v[98:101], v[208:211], v[176:179], v[98:101]
	v_mfma_f32_16x16x32_bf16 v[86:89], v[200:203], v[184:187], v[86:89]
	v_mfma_f32_16x16x32_bf16 v[82:85], v[208:211], v[184:187], v[82:85]
	v_mfma_f32_16x16x32_bf16 v[70:73], v[200:203], v[192:195], v[70:73]
	v_mfma_f32_16x16x32_bf16 v[66:69], v[208:211], v[192:195], v[66:69]
	v_mfma_f32_16x16x32_bf16 v[118:121], v[204:207], v[172:175], v[118:121]
	v_mfma_f32_16x16x32_bf16 v[114:117], v[212:215], v[172:175], v[114:117]
	v_mfma_f32_16x16x32_bf16 v[102:105], v[204:207], v[180:183], v[102:105]
	v_mfma_f32_16x16x32_bf16 v[98:101], v[212:215], v[180:183], v[98:101]
	v_mfma_f32_16x16x32_bf16 v[86:89], v[204:207], v[188:191], v[86:89]
	v_mfma_f32_16x16x32_bf16 v[82:85], v[212:215], v[188:191], v[82:85]
	v_mfma_f32_16x16x32_bf16 v[70:73], v[204:207], v[196:199], v[70:73]
	v_mfma_f32_16x16x32_bf16 v[66:69], v[212:215], v[196:199], v[66:69]
	s_setprio 0
	s_mov_b32 m0, s17
	v_lshl_add_u64 v[220:221], s[22:23], 0, v[130:131]
	s_barrier
	ds_read_b128 v[168:171], v154 offset:16384
	ds_read_b128 v[172:175], v154 offset:17408
	ds_read_b128 v[176:179], v154 offset:18432
	ds_read_b128 v[180:183], v154 offset:19456
	ds_read_b128 v[184:187], v154 offset:20480
	ds_read_b128 v[188:191], v154 offset:21504
	ds_read_b128 v[192:195], v154 offset:22528
	ds_read_b128 v[196:199], v154 offset:23552
	global_load_lds_dwordx4 v[220:221], off
	v_lshl_add_u64 v[222:223], s[22:23], 0, v[134:135]
	s_mov_b32 m0, s31
	s_nop 0
	global_load_lds_dwordx4 v[222:223], off
	s_barrier
	s_waitcnt lgkmcnt(0)
	s_setprio 1
	s_waitcnt lgkmcnt(0)
	v_mfma_f32_16x16x32_bf16 v[62:65], v[148:151], v[168:171], v[62:65]
	v_mfma_f32_16x16x32_bf16 v[58:61], v[160:163], v[168:171], v[58:61]
	v_mfma_f32_16x16x32_bf16 v[46:49], v[148:151], v[176:179], v[46:49]
	v_mfma_f32_16x16x32_bf16 v[42:45], v[160:163], v[176:179], v[42:45]
	v_mfma_f32_16x16x32_bf16 v[30:33], v[148:151], v[184:187], v[30:33]
	v_mfma_f32_16x16x32_bf16 v[26:29], v[160:163], v[184:187], v[26:29]
	v_mfma_f32_16x16x32_bf16 v[14:17], v[148:151], v[192:195], v[14:17]
	v_mfma_f32_16x16x32_bf16 v[10:13], v[160:163], v[192:195], v[10:13]
	v_mfma_f32_16x16x32_bf16 v[62:65], v[156:159], v[172:175], v[62:65]
	v_mfma_f32_16x16x32_bf16 v[58:61], v[164:167], v[172:175], v[58:61]
	v_mfma_f32_16x16x32_bf16 v[46:49], v[156:159], v[180:183], v[46:49]
	v_mfma_f32_16x16x32_bf16 v[42:45], v[164:167], v[180:183], v[42:45]
	v_mfma_f32_16x16x32_bf16 v[30:33], v[156:159], v[188:191], v[30:33]
	v_mfma_f32_16x16x32_bf16 v[26:29], v[164:167], v[188:191], v[26:29]
	v_mfma_f32_16x16x32_bf16 v[14:17], v[156:159], v[196:199], v[14:17]
	v_mfma_f32_16x16x32_bf16 v[10:13], v[164:167], v[196:199], v[10:13]
	s_setprio 0
	s_barrier
; #define PG8_STAGE(bufoff, gbase, voff) do { _Pragma("unroll") for (int _i = 0; _i < 2; ++_i) \
;     __builtin_amdgcn_global_load_lds((const unsigned*)((const char*)(gbase) + (voff)[_i]), (LAS unsigned*)(lds + (bufoff) + ldsw + _i * 8192), 16, 0, 0); } while (0)
; #define PG8_LDA(dst, b, h) do { _Pragma("unroll") for (int m = 0; m < 4; ++m) _Pragma("unroll") for (int k = 0; k < 2; ++k) dst[m][k] = *(const LAS bf16x8*)(lds + PG8_SA(b, h) + aoff + m * 2048 + k * 1024); } while (0)
; #define PG8_LDB(dst, b, h) do { _Pragma("unroll") for (int n = 0; n < 2; ++n) _Pragma("unroll") for (int k = 0; k < 2; ++k) dst[n][k] = *(const LAS bf16x8*)(lds + PG8_SB(b, h) + boff + n * 2048 + k * 1024); } while (0)
; #define PG8_MMA(ai, bj, At, Bt) do { __builtin_amdgcn_s_setprio(1); _Pragma("unroll") for (int m = 0; m < 4; ++m) _Pragma("unroll") for (int n = 0; n < 2; ++n) _Pragma("unroll") for (int k = 0; k < 2; ++k) \
;     acc[ai][bj][m][n] = __builtin_amdgcn_mfma_f32_16x16x32_bf16(Bt[n][k], At[m][k], acc[ai][bj][m][n], 0, 0, 0); __builtin_amdgcn_s_setprio(0); } while (0)
; #define PG8_WAIT_V(n) asm volatile("s_waitcnt vmcnt(" #n ")" ::: "memory")
; #define PG8_WAIT_L(n) asm volatile("s_waitcnt lgkmcnt(" #n ")" ::: "memory")
; #define PG8_BAR __builtin_amdgcn_s_barrier()
; #define PG8_SCHED __builtin_amdgcn_sched_barrier(0)
; template <class Epi>
; DI void gemm_phase(LAS unsigned char* lds, const Gemm g, const StaticOrder& S, const Epi& E) {
;     ...
;       PG8_STAGE(PG8_SB(0, 1), b2 + hstepB, voffB);
;       PG8_WAIT_V(6); PG8_BAR; PG8_MMA(1, 1, At, B1); PG8_BAR;
;       PG8_LDB(B0, 1, 0); PG8_SCHED; PG8_LDA(At, 1, 0); PG8_STAGE(PG8_SA(0, 1), a2 + hstepA, voffA);
;       PG8_WAIT_L(8); PG8_BAR; PG8_WAIT_L(0); PG8_MMA(0, 0, At, B0); PG8_BAR; PG8_SCHED;
;       PG8_LDB(B1, 1, 1); PG8_STAGE(PG8_SB(1, 0), b3, voffB);
;       PG8_BAR; PG8_WAIT_L(0); PG8_MMA(0, 1, At, B1); PG8_BAR;
;       PG8_LDA(At, 1, 1); PG8_STAGE(PG8_SA(1, 0), a3, voffA);
	s_add_u32 s48, s20, 0x80000
	s_addc_u32 s49, s21, 0
	s_add_i32 s47, s40, s30
	v_lshl_add_u64 v[148:149], s[48:49], 0, v[132:133]
	s_mov_b32 m0, s47
	s_nop 0
	global_load_lds_dwordx4 v[148:149], off
	v_lshl_add_u64 v[148:149], s[48:49], 0, v[136:137]
	s_add_i32 m0, s47, 0x2000
	s_nop 0
	global_load_lds_dwordx4 v[148:149], off
	s_waitcnt vmcnt(6)
	s_barrier
	s_setprio 1
	v_mfma_f32_16x16x32_bf16 v[54:57], v[200:203], v[168:171], v[54:57]
	v_mfma_f32_16x16x32_bf16 v[50:53], v[208:211], v[168:171], v[50:53]
	v_mfma_f32_16x16x32_bf16 v[38:41], v[200:203], v[176:179], v[38:41]
	v_mfma_f32_16x16x32_bf16 v[34:37], v[208:211], v[176:179], v[34:37]
	v_mfma_f32_16x16x32_bf16 v[22:25], v[200:203], v[184:187], v[22:25]
	v_mfma_f32_16x16x32_bf16 v[18:21], v[208:211], v[184:187], v[18:21]
	v_mfma_f32_16x16x32_bf16 v[6:9], v[200:203], v[192:195], v[6:9]
	v_mfma_f32_16x16x32_bf16 v[2:5], v[208:211], v[192:195], v[2:5]
	v_mfma_f32_16x16x32_bf16 v[54:57], v[204:207], v[172:175], v[54:57]
	v_mfma_f32_16x16x32_bf16 v[50:53], v[212:215], v[172:175], v[50:53]
	v_mfma_f32_16x16x32_bf16 v[38:41], v[204:207], v[180:183], v[38:41]
	v_mfma_f32_16x16x32_bf16 v[34:37], v[212:215], v[180:183], v[34:37]
	v_mfma_f32_16x16x32_bf16 v[22:25], v[204:207], v[188:191], v[22:25]
	v_mfma_f32_16x16x32_bf16 v[18:21], v[212:215], v[188:191], v[18:21]
	v_mfma_f32_16x16x32_bf16 v[6:9], v[204:207], v[196:199], v[6:9]
	v_mfma_f32_16x16x32_bf16 v[2:5], v[212:215], v[196:199], v[2:5]
	s_setprio 0
	s_add_i32 s47, 0, 0x18000
	v_add_u32_e32 v164, s47, v152
	s_barrier
	ds_read_b128 v[148:151], v164
	ds_read_b128 v[156:159], v164 offset:1024
	ds_read_b128 v[160:163], v164 offset:2048
	ds_read_b128 v[164:167], v164 offset:3072
	s_add_u32 s22, s22, 0x80000
	s_addc_u32 s23, s23, 0
	s_mov_b32 m0, s33
	v_lshl_add_u64 v[200:201], s[22:23], 0, v[130:131]
	ds_read_b128 v[168:171], v154 offset:32768
	ds_read_b128 v[172:175], v154 offset:33792
	ds_read_b128 v[176:179], v154 offset:34816
	ds_read_b128 v[180:183], v154 offset:35840
	ds_read_b128 v[184:187], v154 offset:36864
	ds_read_b128 v[188:191], v154 offset:37888
	ds_read_b128 v[192:195], v154 offset:38912
	ds_read_b128 v[196:199], v154 offset:39936
	global_load_lds_dwordx4 v[200:201], off
	v_lshl_add_u64 v[200:201], s[22:23], 0, v[134:135]
	s_mov_b32 m0, s34
	s_nop 0
	global_load_lds_dwordx4 v[200:201], off
	s_waitcnt lgkmcnt(8)
	s_barrier
	s_waitcnt lgkmcnt(0)
	s_setprio 1
	s_waitcnt lgkmcnt(0)
	v_mfma_f32_16x16x32_bf16 v[126:129], v[148:151], v[168:171], v[126:129]
	v_mfma_f32_16x16x32_bf16 v[122:125], v[160:163], v[168:171], v[122:125]
	v_mfma_f32_16x16x32_bf16 v[110:113], v[148:151], v[176:179], v[110:113]
	v_mfma_f32_16x16x32_bf16 v[106:109], v[160:163], v[176:179], v[106:109]
	v_mfma_f32_16x16x32_bf16 v[94:97], v[148:151], v[184:187], v[94:97]
	v_mfma_f32_16x16x32_bf16 v[90:93], v[160:163], v[184:187], v[90:93]
	v_mfma_f32_16x16x32_bf16 v[78:81], v[148:151], v[192:195], v[78:81]
	v_mfma_f32_16x16x32_bf16 v[74:77], v[160:163], v[192:195], v[74:77]
	v_mfma_f32_16x16x32_bf16 v[126:129], v[156:159], v[172:175], v[126:129]
	v_mfma_f32_16x16x32_bf16 v[122:125], v[164:167], v[172:175], v[122:125]
	v_mfma_f32_16x16x32_bf16 v[110:113], v[156:159], v[180:183], v[110:113]
	v_mfma_f32_16x16x32_bf16 v[106:109], v[164:167], v[180:183], v[106:109]
	v_mfma_f32_16x16x32_bf16 v[94:97], v[156:159], v[188:191], v[94:97]
	v_mfma_f32_16x16x32_bf16 v[90:93], v[164:167], v[188:191], v[90:93]
	v_mfma_f32_16x16x32_bf16 v[78:81], v[156:159], v[196:199], v[78:81]
	v_mfma_f32_16x16x32_bf16 v[74:77], v[164:167], v[196:199], v[74:77]
	s_setprio 0
	s_barrier
	s_add_i32 s22, 0, 0x1c000
	s_add_i32 s23, s47, s30
	v_add_u32_e32 v212, s22, v152
	v_lshl_add_u64 v[216:217], v[216:217], 0, s[2:3]
	s_mov_b32 m0, s23
	ds_read_b128 v[200:203], v212
	ds_read_b128 v[204:207], v212 offset:1024
	ds_read_b128 v[208:211], v212 offset:2048
	ds_read_b128 v[212:215], v212 offset:3072
	global_load_lds_dwordx4 v[216:217], off
	v_lshl_add_u64 v[216:217], v[218:219], 0, s[2:3]
	s_add_i32 m0, s23, 0x2000
	s_nop 0
	global_load_lds_dwordx4 v[216:217], off
	s_barrier
	s_waitcnt lgkmcnt(0)
	s_setprio 1
	s_waitcnt lgkmcnt(0)
	v_mfma_f32_16x16x32_bf16 v[118:121], v[200:203], v[168:171], v[118:121]
	v_mfma_f32_16x16x32_bf16 v[114:117], v[208:211], v[168:171], v[114:117]
	v_mfma_f32_16x16x32_bf16 v[102:105], v[200:203], v[176:179], v[102:105]
	v_mfma_f32_16x16x32_bf16 v[98:101], v[208:211], v[176:179], v[98:101]
	v_mfma_f32_16x16x32_bf16 v[86:89], v[200:203], v[184:187], v[86:89]
	v_mfma_f32_16x16x32_bf16 v[82:85], v[208:211], v[184:187], v[82:85]
	v_mfma_f32_16x16x32_bf16 v[70:73], v[200:203], v[192:195], v[70:73]
	v_mfma_f32_16x16x32_bf16 v[66:69], v[208:211], v[192:195], v[66:69]
	v_mfma_f32_16x16x32_bf16 v[118:121], v[204:207], v[172:175], v[118:121]
	v_mfma_f32_16x16x32_bf16 v[114:117], v[212:215], v[172:175], v[114:117]
	v_mfma_f32_16x16x32_bf16 v[102:105], v[204:207], v[180:183], v[102:105]
	v_mfma_f32_16x16x32_bf16 v[98:101], v[212:215], v[180:183], v[98:101]
	v_mfma_f32_16x16x32_bf16 v[86:89], v[204:207], v[188:191], v[86:89]
	v_mfma_f32_16x16x32_bf16 v[82:85], v[212:215], v[188:191], v[82:85]
	v_mfma_f32_16x16x32_bf16 v[70:73], v[204:207], v[196:199], v[70:73]
	v_mfma_f32_16x16x32_bf16 v[66:69], v[212:215], v[196:199], v[66:69]
	s_setprio 0
	s_mov_b32 m0, s36
	v_lshl_add_u64 v[216:217], v[220:221], 0, s[2:3]
	s_barrier
	ds_read_b128 v[168:171], v154 offset:49152
	ds_read_b128 v[172:175], v154 offset:50176
	ds_read_b128 v[176:179], v154 offset:51200
	ds_read_b128 v[180:183], v154 offset:52224
	ds_read_b128 v[184:187], v154 offset:53248
	ds_read_b128 v[188:191], v154 offset:54272
	ds_read_b128 v[192:195], v154 offset:55296
	ds_read_b128 v[196:199], v154 offset:56320
	global_load_lds_dwordx4 v[216:217], off
	v_lshl_add_u64 v[216:217], v[222:223], 0, s[2:3]
	s_mov_b32 m0, s37
	s_nop 0
	global_load_lds_dwordx4 v[216:217], off
	s_barrier
; #define PG8_BAR __builtin_amdgcn_s_barrier()
; template <class Epi>
; DI void gemm_phase(LAS unsigned char* lds, const Gemm g, const StaticOrder& S, const Epi& E) {
;     ...
;       PG8_WAIT_V(6); PG8_BAR; PG8_MMA(1, 1, At, B1); PG8_BAR;
;       PG8_LDB(B0, 1, 0); PG8_SCHED; PG8_LDA(At, 1, 0); PG8_STAGE(PG8_SA(0, 1), a2 + hstepA, voffA);
;       PG8_WAIT_L(8); PG8_BAR; PG8_WAIT_L(0); PG8_MMA(0, 0, At, B0); PG8_BAR; PG8_SCHED;
;       PG8_LDB(B1, 1, 1); PG8_STAGE(PG8_SB(1, 0), b3, voffB);
;       PG8_BAR; PG8_WAIT_L(0); PG8_MMA(0, 1, At, B1); PG8_BAR;
;       PG8_LDA(At, 1, 1); PG8_STAGE(PG8_SA(1, 0), a3, voffA);
;       PG8_BAR; PG8_WAIT_L(0); PG8_MMA(1, 0, At, B0); PG8_BAR; PG8_SCHED;
;       PG8_STAGE(PG8_SB(1, 1), b3 + hstepB, voffB);
;       PG8_WAIT_V(6); PG8_BAR; PG8_MMA(1, 1, At, B1); PG8_BAR;
;   DI void operator()(const f32x4 (&acc)[2][2][4][2], const pg8::Unit& u, int wr, int wc, int fr, int fq) const {
;     ...
;       for (int m = 0; m < 4; ++m) {
;         const int row = u.pm * 256 + ai * 128 + wr * 64 + m * 16 + fr;
;         const int grow = rowbase + row;
;         float rs = 1.f;
;         if (MODE == EP_IN) rs = ((const float*)(ws + OFF_RS0))[grow];
;         if (MODE == EP_UP) rs = ((const float*)(ws + OFF_RS2))[grow];
;         if (MODE == EP_Q || MODE == EP_KV) {
;           const f32x4* sp = (const f32x4*)(ws + OFF_SSQA) + (size_t)grow * 4 + (MODE == EP_KV ? 2 : 0);
;           const f32x4 s0 = sp[0], s1 = sp[1];
;           const float ss = (s0[0] + s0[1]) + (s0[2] + s0[3]) + (s1[0] + s1[1]) + (s1[2] + s1[3]);
;           rs = __builtin_amdgcn_rsqf(ss * (1.0f / 512) + EPS);
;           if (MODE == EP_Q) rs *= QSCALE;
;         }
;         float ssq = 0.f;
; #pragma unroll
;         for (int bj = 0; bj < 2; ++bj) {
;           f32x4 v0 = acc[ai][bj][m][0] * rs, v1 = acc[ai][bj][m][1] * rs;
;           if (MODE == EP_IN || MODE == EP_MIX || MODE == EP_DOWN) {
; #pragma unroll
;             for (int j = 0; j < 4; ++j) ssq += v0[j] * v0[j] + v1[j] * v1[j];
;           }
;           if (MODE == EP_UP) {
; #pragma unroll
;             for (int j = 0; j < 4; ++j) { float a = fmaxf(v0[j], 0.f), b = fmaxf(v1[j], 0.f); v0[j] = a * a; v1[j] = b * b; }
;           }
;           bf16_t* dst;
;           const int ct = bj * 128 + cl;
;           if (MODE == EP_IN) {
;             if (pn < 4) dst = (bf16_t*)(ws + OFF_PROJA) + (size_t)grow * 1024 + pn * 256 + ct;
	s_waitcnt lgkmcnt(0)
	s_setprio 1
	s_waitcnt lgkmcnt(0)
	v_mfma_f32_16x16x32_bf16 v[62:65], v[148:151], v[168:171], v[62:65]
	v_mfma_f32_16x16x32_bf16 v[58:61], v[160:163], v[168:171], v[58:61]
	v_mfma_f32_16x16x32_bf16 v[46:49], v[148:151], v[176:179], v[46:49]
	v_mfma_f32_16x16x32_bf16 v[42:45], v[160:163], v[176:179], v[42:45]
	v_mfma_f32_16x16x32_bf16 v[30:33], v[148:151], v[184:187], v[30:33]
	v_mfma_f32_16x16x32_bf16 v[26:29], v[160:163], v[184:187], v[26:29]
	v_mfma_f32_16x16x32_bf16 v[14:17], v[148:151], v[192:195], v[14:17]
	v_mfma_f32_16x16x32_bf16 v[10:13], v[160:163], v[192:195], v[10:13]
	v_mfma_f32_16x16x32_bf16 v[62:65], v[156:159], v[172:175], v[62:65]
	v_mfma_f32_16x16x32_bf16 v[58:61], v[164:167], v[172:175], v[58:61]
	v_mfma_f32_16x16x32_bf16 v[46:49], v[156:159], v[180:183], v[46:49]
	v_mfma_f32_16x16x32_bf16 v[42:45], v[164:167], v[180:183], v[42:45]
	v_mfma_f32_16x16x32_bf16 v[30:33], v[156:159], v[188:191], v[30:33]
	v_mfma_f32_16x16x32_bf16 v[26:29], v[164:167], v[188:191], v[26:29]
	v_mfma_f32_16x16x32_bf16 v[14:17], v[156:159], v[196:199], v[14:17]
	v_mfma_f32_16x16x32_bf16 v[10:13], v[164:167], v[196:199], v[10:13]
	s_setprio 0
	s_barrier
	s_add_u32 s20, s20, 0x80080
	s_addc_u32 s21, s21, 0
	s_add_i32 s22, s22, s30
	v_lshl_add_u64 v[148:149], s[20:21], 0, v[132:133]
	s_mov_b32 m0, s22
	s_nop 0
	global_load_lds_dwordx4 v[148:149], off
	v_lshl_add_u64 v[148:149], s[20:21], 0, v[136:137]
	s_add_i32 m0, s22, 0x2000
	s_nop 0
	global_load_lds_dwordx4 v[148:149], off
	s_waitcnt vmcnt(6)
	s_barrier
	s_setprio 1
	v_mfma_f32_16x16x32_bf16 v[54:57], v[200:203], v[168:171], v[54:57]
	v_mfma_f32_16x16x32_bf16 v[50:53], v[208:211], v[168:171], v[50:53]
	v_mfma_f32_16x16x32_bf16 v[38:41], v[200:203], v[176:179], v[38:41]
	v_mfma_f32_16x16x32_bf16 v[34:37], v[208:211], v[176:179], v[34:37]
	v_mfma_f32_16x16x32_bf16 v[22:25], v[200:203], v[184:187], v[22:25]
	v_mfma_f32_16x16x32_bf16 v[18:21], v[208:211], v[184:187], v[18:21]
	v_mfma_f32_16x16x32_bf16 v[6:9], v[200:203], v[192:195], v[6:9]
	v_mfma_f32_16x16x32_bf16 v[2:5], v[208:211], v[192:195], v[2:5]
	v_mfma_f32_16x16x32_bf16 v[54:57], v[204:207], v[172:175], v[54:57]
	v_mfma_f32_16x16x32_bf16 v[50:53], v[212:215], v[172:175], v[50:53]
	v_mfma_f32_16x16x32_bf16 v[38:41], v[204:207], v[180:183], v[38:41]
	v_mfma_f32_16x16x32_bf16 v[34:37], v[212:215], v[180:183], v[34:37]
	v_mfma_f32_16x16x32_bf16 v[22:25], v[204:207], v[188:191], v[22:25]
	v_mfma_f32_16x16x32_bf16 v[18:21], v[212:215], v[188:191], v[18:21]
	v_mfma_f32_16x16x32_bf16 v[6:9], v[204:207], v[196:199], v[6:9]
	v_mfma_f32_16x16x32_bf16 v[2:5], v[212:215], v[196:199], v[2:5]
	s_setprio 0
	s_add_i32 s46, s46, 2
	s_add_u32 s18, s18, 0x100
	s_addc_u32 s19, s19, 0
	s_add_u32 s44, s44, 0x100
	s_addc_u32 s45, s45, 0
	s_cmp_gt_u32 s46, 29
	s_barrier
	s_cbranch_scc0 .LBB0_1015
	v_lshl_add_u32 v148, s16, 8, v1
	v_ashrrev_i32_e32 v149, 31, v148
	v_lshl_add_u64 v[150:151], v[148:149], 2, s[4:5]
	v_add_co_u32_e32 v150, vcc, 0x10000, v150
	s_lshl_b32 s18, s41, 8
	s_nop 0
	v_addc_co_u32_e32 v151, vcc, 0, v151, vcc
	s_nop 0
	s_ashr_i32 s19, s18, 31
	v_lshlrev_b64 v[158:159], 14, v[148:149]
	s_lshl_b64 s[18:19], s[18:19], 1
	v_lshl_add_u64 v[158:159], s[6:7], 0, v[158:159]
	v_lshl_add_u64 v[158:159], v[158:159], 0, s[18:19]
	v_lshl_add_u64 v[158:159], v[158:159], 0, v[138:139]
	s_and_b64 vcc, exec, s[0:1]
	s_mov_b32 s41, s8
	s_mov_b32 s16, s10
	s_mov_b64 s[20:21], s[14:15]
	s_mov_b64 s[22:23], s[12:13]
	v_mov_b32_e32 v156, v247
	v_pk_mul_f32 v[128:129], v[128:129], v[156:157] op_sel_hi:[1,0]
	v_pk_mul_f32 v[126:127], v[126:127], v[156:157] op_sel_hi:[1,0]
	v_pk_mul_f32 v[124:125], v[124:125], v[156:157] op_sel_hi:[1,0]
	v_pk_mul_f32 v[122:123], v[122:123], v[156:157] op_sel_hi:[1,0]
	v_pk_mul_f32 v[120:121], v[120:121], v[156:157] op_sel_hi:[1,0]
	v_pk_mul_f32 v[118:119], v[118:119], v[156:157] op_sel_hi:[1,0]
	v_pk_mul_f32 v[116:117], v[116:117], v[156:157] op_sel_hi:[1,0]
	v_pk_mul_f32 v[114:115], v[114:115], v[156:157] op_sel_hi:[1,0]
	v_max_f32_e32 v126, 0, v126
	v_max_f32_e32 v122, 0, v122
	v_max_f32_e32 v127, 0, v127
	v_max_f32_e32 v123, 0, v123
	v_max_f32_e32 v128, 0, v128
	v_max_f32_e32 v124, 0, v124
	v_max_f32_e32 v129, 0, v129
	v_max_f32_e32 v125, 0, v125
	v_max_f32_e32 v118, 0, v118
	v_max_f32_e32 v114, 0, v114
	v_max_f32_e32 v119, 0, v119
	v_max_f32_e32 v115, 0, v115
	v_max_f32_e32 v120, 0, v120
	v_max_f32_e32 v116, 0, v116
	v_max_f32_e32 v121, 0, v121
	v_max_f32_e32 v117, 0, v117
	v_pk_mul_f32 v[126:127], v[126:127], v[126:127]
	v_pk_mul_f32 v[122:123], v[122:123], v[122:123]
	v_pk_mul_f32 v[128:129], v[128:129], v[128:129]
	v_pk_mul_f32 v[124:125], v[124:125], v[124:125]
	v_pk_mul_f32 v[118:119], v[118:119], v[118:119]
	v_pk_mul_f32 v[156:157], v[114:115], v[114:115]
	v_pk_mul_f32 v[120:121], v[120:121], v[120:121]
	v_pk_mul_f32 v[160:161], v[116:117], v[116:117]
	v_cvt_pk_bf16_f32 v114, v126, v127
	v_cvt_pk_bf16_f32 v115, v128, v129
	v_cvt_pk_bf16_f32 v116, v122, v123
	v_cvt_pk_bf16_f32 v117, v124, v125
	v_cvt_pk_bf16_f32 v118, v118, v119
	v_cvt_pk_bf16_f32 v119, v120, v121
	v_cvt_pk_bf16_f32 v120, v156, v157
	v_cvt_pk_bf16_f32 v121, v160, v161
	global_store_dwordx4 v[158:159], v[114:117], off
	global_store_dwordx4 v[158:159], v[118:121], off offset:256
	s_nop 0
	v_or_b32_e32 v116, 16, v148
	v_ashrrev_i32_e32 v117, 31, v116
	v_lshlrev_b64 v[116:117], 14, v[116:117]
	v_lshl_add_u64 v[116:117], s[6:7], 0, v[116:117]
	v_lshl_add_u64 v[116:117], v[116:117], 0, s[18:19]
	v_lshl_add_u64 v[116:117], v[116:117], 0, v[138:139]
	v_mov_b32_e32 v114, v240
	v_pk_mul_f32 v[112:113], v[112:113], v[114:115] op_sel_hi:[1,0]
;   DI void operator()(const f32x4 (&acc)[2][2][4][2], const pg8::Unit& u, int wr, int wc, int fr, int fq) const {
;     ...
;           f32x4 v0 = acc[ai][bj][m][0] * rs, v1 = acc[ai][bj][m][1] * rs;
;           if (MODE == EP_IN || MODE == EP_MIX || MODE == EP_DOWN) {
; #pragma unroll
;             for (int j = 0; j < 4; ++j) ssq += v0[j] * v0[j] + v1[j] * v1[j];
;           }
;           if (MODE == EP_UP) {
; #pragma unroll
;             for (int j = 0; j < 4; ++j) { float a = fmaxf(v0[j], 0.f), b = fmaxf(v1[j], 0.f); v0[j] = a * a; v1[j] = b * b; }
;           }
;           bf16_t* dst;
;           const int ct = bj * 128 + cl;
;           if (MODE == EP_IN) {
;             if (pn < 4) dst = (bf16_t*)(ws + OFF_PROJA) + (size_t)grow * 1024 + pn * 256 + ct;
;             else if (pn < 16) dst = (bf16_t*)(ws + OFF_PROJG) + (size_t)grow * 3072 + (pn - 4) * 256 + ct;
;             else dst = (bf16_t*)(ws + OFF_PROJS) + (size_t)grow * 256 + ct;
;           } else if (MODE == EP_Q) {
;             if (pn < 4) dst = (bf16_t*)(dout + DO_Q) + (size_t)grow * 1536 + (pn * 2 + bj) * 192 + cl;
;             else {
;               const int mm = (pn - 4) * 256 + ct, h = mm >> 6, r = mm & 63;
;               dst = (bf16_t*)(dout + DO_Q) + (size_t)grow * 1536 + h * 192 + 128 + r;
;               const int pos = grow < TP ? (grow & 4095) : grow - TP;
;               const f32x4* tb = (const f32x4*)((const f32x2*)(ws + OFF_ROPE) + pos * 32 + (r >> 1));
;               const f32x4 t0 = tb[0], t1 = tb[1];
;               f32x4 o0, o1;
;               o0[0] = v0[0] * t0[0] - v0[1] * t0[1]; o0[1] = v0[1] * t0[0] + v0[0] * t0[1];
;               o0[2] = v0[2] * t0[2] - v0[3] * t0[3]; o0[3] = v0[3] * t0[2] + v0[2] * t0[3];
;               o1[0] = v1[0] * t1[0] - v1[1] * t1[1]; o1[1] = v1[1] * t1[0] + v1[0] * t1[1];
;               o1[2] = v1[2] * t1[2] - v1[3] * t1[3]; o1[3] = v1[3] * t1[2] + v1[2] * t1[3];
;               v0 = o0; v1 = o1;
;             }
;           } else if (MODE == EP_KV) {
;             dst = (bf16_t*)(ws + OFF_XB) + (size_t)grow * 2048 + pn * 256 + ct;
;           } else if (MODE == EP_MIX) {
;             dst = (bf16_t*)(ws + OFF_MIX) + (size_t)grow * 2048 + pn * 256 + ct;
;           } else if (MODE == EP_UP) {
;             dst = (bf16_t*)(ws + OFF_U) + (size_t)row * 8192 + pn * 256 + ct;
;           } else {
	v_pk_mul_f32 v[110:111], v[110:111], v[114:115] op_sel_hi:[1,0]
	v_pk_mul_f32 v[108:109], v[108:109], v[114:115] op_sel_hi:[1,0]
	v_pk_mul_f32 v[106:107], v[106:107], v[114:115] op_sel_hi:[1,0]
	v_pk_mul_f32 v[104:105], v[104:105], v[114:115] op_sel_hi:[1,0]
	v_pk_mul_f32 v[102:103], v[102:103], v[114:115] op_sel_hi:[1,0]
	v_pk_mul_f32 v[100:101], v[100:101], v[114:115] op_sel_hi:[1,0]
	v_pk_mul_f32 v[98:99], v[98:99], v[114:115] op_sel_hi:[1,0]
	v_max_f32_e32 v110, 0, v110
	v_max_f32_e32 v106, 0, v106
	v_max_f32_e32 v111, 0, v111
	v_max_f32_e32 v107, 0, v107
	v_max_f32_e32 v112, 0, v112
	v_max_f32_e32 v108, 0, v108
	v_max_f32_e32 v113, 0, v113
	v_max_f32_e32 v109, 0, v109
	v_max_f32_e32 v102, 0, v102
	v_max_f32_e32 v98, 0, v98
	v_max_f32_e32 v103, 0, v103
	v_max_f32_e32 v99, 0, v99
	v_max_f32_e32 v104, 0, v104
	v_max_f32_e32 v100, 0, v100
	v_max_f32_e32 v105, 0, v105
	v_max_f32_e32 v101, 0, v101
	v_pk_mul_f32 v[110:111], v[110:111], v[110:111]
	v_pk_mul_f32 v[106:107], v[106:107], v[106:107]
	v_pk_mul_f32 v[112:113], v[112:113], v[112:113]
	v_pk_mul_f32 v[108:109], v[108:109], v[108:109]
	v_pk_mul_f32 v[102:103], v[102:103], v[102:103]
	v_pk_mul_f32 v[114:115], v[98:99], v[98:99]
	v_pk_mul_f32 v[104:105], v[104:105], v[104:105]
	v_pk_mul_f32 v[118:119], v[100:101], v[100:101]
	v_cvt_pk_bf16_f32 v98, v110, v111
	v_cvt_pk_bf16_f32 v99, v112, v113
	v_cvt_pk_bf16_f32 v100, v106, v107
	v_cvt_pk_bf16_f32 v101, v108, v109
	v_cvt_pk_bf16_f32 v102, v102, v103
	v_cvt_pk_bf16_f32 v103, v104, v105
	v_cvt_pk_bf16_f32 v104, v114, v115
	v_cvt_pk_bf16_f32 v105, v118, v119
	global_store_dwordx4 v[116:117], v[98:101], off
	global_store_dwordx4 v[116:117], v[102:105], off offset:256
	s_nop 0
	v_or_b32_e32 v100, 32, v148
	v_ashrrev_i32_e32 v101, 31, v100
	v_lshlrev_b64 v[100:101], 14, v[100:101]
	v_lshl_add_u64 v[100:101], s[6:7], 0, v[100:101]
	v_lshl_add_u64 v[100:101], v[100:101], 0, s[18:19]
	v_lshl_add_u64 v[100:101], v[100:101], 0, v[138:139]
	v_mov_b32_e32 v98, v241
	v_pk_mul_f32 v[96:97], v[96:97], v[98:99] op_sel_hi:[1,0]
	v_pk_mul_f32 v[94:95], v[94:95], v[98:99] op_sel_hi:[1,0]
	v_pk_mul_f32 v[92:93], v[92:93], v[98:99] op_sel_hi:[1,0]
	v_pk_mul_f32 v[90:91], v[90:91], v[98:99] op_sel_hi:[1,0]
	v_pk_mul_f32 v[88:89], v[88:89], v[98:99] op_sel_hi:[1,0]
	v_pk_mul_f32 v[86:87], v[86:87], v[98:99] op_sel_hi:[1,0]
	v_pk_mul_f32 v[84:85], v[84:85], v[98:99] op_sel_hi:[1,0]
	v_pk_mul_f32 v[82:83], v[82:83], v[98:99] op_sel_hi:[1,0]
	v_max_f32_e32 v94, 0, v94
	v_max_f32_e32 v90, 0, v90
	v_max_f32_e32 v95, 0, v95
	v_max_f32_e32 v91, 0, v91
	v_max_f32_e32 v96, 0, v96
	v_max_f32_e32 v92, 0, v92
	v_max_f32_e32 v97, 0, v97
	v_max_f32_e32 v93, 0, v93
	v_max_f32_e32 v86, 0, v86
	v_max_f32_e32 v82, 0, v82
	v_max_f32_e32 v87, 0, v87
	v_max_f32_e32 v83, 0, v83
	v_max_f32_e32 v88, 0, v88
	v_max_f32_e32 v84, 0, v84
	v_max_f32_e32 v89, 0, v89
	v_max_f32_e32 v85, 0, v85
	v_pk_mul_f32 v[94:95], v[94:95], v[94:95]
	v_pk_mul_f32 v[90:91], v[90:91], v[90:91]
	v_pk_mul_f32 v[96:97], v[96:97], v[96:97]
	v_pk_mul_f32 v[92:93], v[92:93], v[92:93]
	v_pk_mul_f32 v[86:87], v[86:87], v[86:87]
	v_pk_mul_f32 v[98:99], v[82:83], v[82:83]
	v_pk_mul_f32 v[88:89], v[88:89], v[88:89]
	v_pk_mul_f32 v[102:103], v[84:85], v[84:85]
	v_cvt_pk_bf16_f32 v82, v94, v95
	v_cvt_pk_bf16_f32 v83, v96, v97
	v_cvt_pk_bf16_f32 v84, v90, v91
	v_cvt_pk_bf16_f32 v85, v92, v93
	v_cvt_pk_bf16_f32 v86, v86, v87
	v_cvt_pk_bf16_f32 v87, v88, v89
	v_cvt_pk_bf16_f32 v88, v98, v99
	v_cvt_pk_bf16_f32 v89, v102, v103
	global_store_dwordx4 v[100:101], v[82:85], off
	global_store_dwordx4 v[100:101], v[86:89], off offset:256
	s_nop 0
	v_or_b32_e32 v84, 48, v148
	v_ashrrev_i32_e32 v85, 31, v84
	v_lshlrev_b64 v[84:85], 14, v[84:85]
	v_lshl_add_u64 v[84:85], s[6:7], 0, v[84:85]
	v_add_u32_e32 v86, 0x4080, v148
	v_lshl_add_u64 v[84:85], v[84:85], 0, s[18:19]
	v_ashrrev_i32_e32 v87, 31, v86
	v_lshl_add_u64 v[84:85], v[84:85], 0, v[138:139]
	v_lshl_add_u64 v[86:87], v[86:87], 2, s[4:5]
	v_mov_b32_e32 v82, v242
	v_pk_mul_f32 v[80:81], v[80:81], v[82:83] op_sel_hi:[1,0]
	v_pk_mul_f32 v[78:79], v[78:79], v[82:83] op_sel_hi:[1,0]
	v_pk_mul_f32 v[76:77], v[76:77], v[82:83] op_sel_hi:[1,0]
	v_pk_mul_f32 v[74:75], v[74:75], v[82:83] op_sel_hi:[1,0]
	v_pk_mul_f32 v[72:73], v[72:73], v[82:83] op_sel_hi:[1,0]
	v_pk_mul_f32 v[70:71], v[70:71], v[82:83] op_sel_hi:[1,0]
	v_pk_mul_f32 v[68:69], v[68:69], v[82:83] op_sel_hi:[1,0]
	v_pk_mul_f32 v[66:67], v[66:67], v[82:83] op_sel_hi:[1,0]
	v_max_f32_e32 v78, 0, v78
	v_max_f32_e32 v74, 0, v74
	v_max_f32_e32 v79, 0, v79
	v_max_f32_e32 v75, 0, v75
	v_max_f32_e32 v80, 0, v80
	v_max_f32_e32 v76, 0, v76
	v_max_f32_e32 v81, 0, v81
	v_max_f32_e32 v77, 0, v77
	v_max_f32_e32 v70, 0, v70
	v_max_f32_e32 v66, 0, v66
	v_max_f32_e32 v71, 0, v71
	v_max_f32_e32 v67, 0, v67
	v_max_f32_e32 v72, 0, v72
	v_max_f32_e32 v68, 0, v68
	v_max_f32_e32 v73, 0, v73
	v_max_f32_e32 v69, 0, v69
	v_pk_mul_f32 v[78:79], v[78:79], v[78:79]
	v_pk_mul_f32 v[74:75], v[74:75], v[74:75]
	v_pk_mul_f32 v[80:81], v[80:81], v[80:81]
	v_pk_mul_f32 v[76:77], v[76:77], v[76:77]
	v_pk_mul_f32 v[70:71], v[70:71], v[70:71]
	v_pk_mul_f32 v[82:83], v[66:67], v[66:67]
	v_pk_mul_f32 v[72:73], v[72:73], v[72:73]
	v_pk_mul_f32 v[88:89], v[68:69], v[68:69]
	v_cvt_pk_bf16_f32 v66, v78, v79
	v_cvt_pk_bf16_f32 v67, v80, v81
	v_cvt_pk_bf16_f32 v68, v74, v75
	v_cvt_pk_bf16_f32 v69, v76, v77
	v_cvt_pk_bf16_f32 v70, v70, v71
	v_cvt_pk_bf16_f32 v71, v72, v73
	v_cvt_pk_bf16_f32 v72, v82, v83
	v_cvt_pk_bf16_f32 v73, v88, v89
	global_store_dwordx4 v[84:85], v[66:69], off
	global_store_dwordx4 v[84:85], v[70:73], off offset:256
	s_nop 0
	v_add_u32_e32 v68, 0x80, v148
;   DI void operator()(const f32x4 (&acc)[2][2][4][2], const pg8::Unit& u, int wr, int wc, int fr, int fq) const {
;     ...
;           f32x4 v0 = acc[ai][bj][m][0] * rs, v1 = acc[ai][bj][m][1] * rs;
;           if (MODE == EP_IN || MODE == EP_MIX || MODE == EP_DOWN) {
; #pragma unroll
;             for (int j = 0; j < 4; ++j) ssq += v0[j] * v0[j] + v1[j] * v1[j];
;           }
;           if (MODE == EP_UP) {
; #pragma unroll
;             for (int j = 0; j < 4; ++j) { float a = fmaxf(v0[j], 0.f), b = fmaxf(v1[j], 0.f); v0[j] = a * a; v1[j] = b * b; }
;           }
;           bf16_t* dst;
;           const int ct = bj * 128 + cl;
;           if (MODE == EP_IN) {
;             if (pn < 4) dst = (bf16_t*)(ws + OFF_PROJA) + (size_t)grow * 1024 + pn * 256 + ct;
;             else if (pn < 16) dst = (bf16_t*)(ws + OFF_PROJG) + (size_t)grow * 3072 + (pn - 4) * 256 + ct;
;             else dst = (bf16_t*)(ws + OFF_PROJS) + (size_t)grow * 256 + ct;
;           } else if (MODE == EP_Q) {
;             if (pn < 4) dst = (bf16_t*)(dout + DO_Q) + (size_t)grow * 1536 + (pn * 2 + bj) * 192 + cl;
;             else {
;               const int mm = (pn - 4) * 256 + ct, h = mm >> 6, r = mm & 63;
;               dst = (bf16_t*)(dout + DO_Q) + (size_t)grow * 1536 + h * 192 + 128 + r;
;               const int pos = grow < TP ? (grow & 4095) : grow - TP;
;               const f32x4* tb = (const f32x4*)((const f32x2*)(ws + OFF_ROPE) + pos * 32 + (r >> 1));
;               const f32x4 t0 = tb[0], t1 = tb[1];
;               f32x4 o0, o1;
;               o0[0] = v0[0] * t0[0] - v0[1] * t0[1]; o0[1] = v0[1] * t0[0] + v0[0] * t0[1];
;               o0[2] = v0[2] * t0[2] - v0[3] * t0[3]; o0[3] = v0[3] * t0[2] + v0[2] * t0[3];
;               o1[0] = v1[0] * t1[0] - v1[1] * t1[1]; o1[1] = v1[1] * t1[0] + v1[0] * t1[1];
;               o1[2] = v1[2] * t1[2] - v1[3] * t1[3]; o1[3] = v1[3] * t1[2] + v1[2] * t1[3];
;               v0 = o0; v1 = o1;
;             }
;           } else if (MODE == EP_KV) {
;             dst = (bf16_t*)(ws + OFF_XB) + (size_t)grow * 2048 + pn * 256 + ct;
;           } else if (MODE == EP_MIX) {
;             dst = (bf16_t*)(ws + OFF_MIX) + (size_t)grow * 2048 + pn * 256 + ct;
;           } else if (MODE == EP_UP) {
;             dst = (bf16_t*)(ws + OFF_U) + (size_t)row * 8192 + pn * 256 + ct;
;           } else {
	v_ashrrev_i32_e32 v69, 31, v68
	v_lshlrev_b64 v[68:69], 14, v[68:69]
	v_lshl_add_u64 v[68:69], s[6:7], 0, v[68:69]
	v_add_u32_e32 v70, 0x4090, v148
	v_lshl_add_u64 v[68:69], v[68:69], 0, s[18:19]
	v_ashrrev_i32_e32 v71, 31, v70
	v_lshl_add_u64 v[68:69], v[68:69], 0, v[138:139]
	v_lshl_add_u64 v[70:71], v[70:71], 2, s[4:5]
	v_mov_b32_e32 v66, v243
	v_pk_mul_f32 v[64:65], v[64:65], v[66:67] op_sel_hi:[1,0]
	v_pk_mul_f32 v[62:63], v[62:63], v[66:67] op_sel_hi:[1,0]
	v_pk_mul_f32 v[60:61], v[60:61], v[66:67] op_sel_hi:[1,0]
	v_pk_mul_f32 v[58:59], v[58:59], v[66:67] op_sel_hi:[1,0]
	v_pk_mul_f32 v[56:57], v[56:57], v[66:67] op_sel_hi:[1,0]
	v_pk_mul_f32 v[54:55], v[54:55], v[66:67] op_sel_hi:[1,0]
	v_pk_mul_f32 v[52:53], v[52:53], v[66:67] op_sel_hi:[1,0]
	v_pk_mul_f32 v[50:51], v[50:51], v[66:67] op_sel_hi:[1,0]
	v_max_f32_e32 v62, 0, v62
	v_max_f32_e32 v58, 0, v58
	v_max_f32_e32 v63, 0, v63
	v_max_f32_e32 v59, 0, v59
	v_max_f32_e32 v64, 0, v64
	v_max_f32_e32 v60, 0, v60
	v_max_f32_e32 v65, 0, v65
	v_max_f32_e32 v61, 0, v61
	v_max_f32_e32 v54, 0, v54
	v_max_f32_e32 v50, 0, v50
	v_max_f32_e32 v55, 0, v55
	v_max_f32_e32 v51, 0, v51
	v_max_f32_e32 v56, 0, v56
	v_max_f32_e32 v52, 0, v52
	v_max_f32_e32 v57, 0, v57
	v_max_f32_e32 v53, 0, v53
	v_pk_mul_f32 v[62:63], v[62:63], v[62:63]
	v_pk_mul_f32 v[58:59], v[58:59], v[58:59]
	v_pk_mul_f32 v[64:65], v[64:65], v[64:65]
	v_pk_mul_f32 v[60:61], v[60:61], v[60:61]
	v_pk_mul_f32 v[54:55], v[54:55], v[54:55]
	v_pk_mul_f32 v[66:67], v[50:51], v[50:51]
	v_pk_mul_f32 v[56:57], v[56:57], v[56:57]
	v_pk_mul_f32 v[72:73], v[52:53], v[52:53]
	v_cvt_pk_bf16_f32 v50, v62, v63
	v_cvt_pk_bf16_f32 v51, v64, v65
	v_cvt_pk_bf16_f32 v52, v58, v59
	v_cvt_pk_bf16_f32 v53, v60, v61
	v_cvt_pk_bf16_f32 v54, v54, v55
	v_cvt_pk_bf16_f32 v55, v56, v57
	v_cvt_pk_bf16_f32 v56, v66, v67
	v_cvt_pk_bf16_f32 v57, v72, v73
	global_store_dwordx4 v[68:69], v[50:53], off
	global_store_dwordx4 v[68:69], v[54:57], off offset:256
	s_nop 0
	v_add_u32_e32 v52, 0x90, v148
	v_ashrrev_i32_e32 v53, 31, v52
	v_lshlrev_b64 v[52:53], 14, v[52:53]
	v_lshl_add_u64 v[52:53], s[6:7], 0, v[52:53]
	v_add_u32_e32 v54, 0x40a0, v148
	v_lshl_add_u64 v[52:53], v[52:53], 0, s[18:19]
	v_ashrrev_i32_e32 v55, 31, v54
	v_lshl_add_u64 v[52:53], v[52:53], 0, v[138:139]
	v_lshl_add_u64 v[54:55], v[54:55], 2, s[4:5]
	v_mov_b32_e32 v50, v244
	v_pk_mul_f32 v[48:49], v[48:49], v[50:51] op_sel_hi:[1,0]
	v_pk_mul_f32 v[46:47], v[46:47], v[50:51] op_sel_hi:[1,0]
	v_pk_mul_f32 v[44:45], v[44:45], v[50:51] op_sel_hi:[1,0]
	v_pk_mul_f32 v[42:43], v[42:43], v[50:51] op_sel_hi:[1,0]
	v_pk_mul_f32 v[40:41], v[40:41], v[50:51] op_sel_hi:[1,0]
	v_pk_mul_f32 v[38:39], v[38:39], v[50:51] op_sel_hi:[1,0]
	v_pk_mul_f32 v[36:37], v[36:37], v[50:51] op_sel_hi:[1,0]
	v_pk_mul_f32 v[34:35], v[34:35], v[50:51] op_sel_hi:[1,0]
	v_max_f32_e32 v46, 0, v46
	v_max_f32_e32 v42, 0, v42
	v_max_f32_e32 v47, 0, v47
	v_max_f32_e32 v43, 0, v43
	v_max_f32_e32 v48, 0, v48
	v_max_f32_e32 v44, 0, v44
	v_max_f32_e32 v49, 0, v49
	v_max_f32_e32 v45, 0, v45
	v_max_f32_e32 v38, 0, v38
	v_max_f32_e32 v34, 0, v34
	v_max_f32_e32 v39, 0, v39
	v_max_f32_e32 v35, 0, v35
	v_max_f32_e32 v40, 0, v40
	v_max_f32_e32 v36, 0, v36
	v_max_f32_e32 v41, 0, v41
	v_max_f32_e32 v37, 0, v37
	v_pk_mul_f32 v[46:47], v[46:47], v[46:47]
	v_pk_mul_f32 v[42:43], v[42:43], v[42:43]
	v_pk_mul_f32 v[48:49], v[48:49], v[48:49]
	v_pk_mul_f32 v[44:45], v[44:45], v[44:45]
	v_pk_mul_f32 v[38:39], v[38:39], v[38:39]
	v_pk_mul_f32 v[50:51], v[34:35], v[34:35]
	v_pk_mul_f32 v[40:41], v[40:41], v[40:41]
	v_pk_mul_f32 v[56:57], v[36:37], v[36:37]
	v_cvt_pk_bf16_f32 v34, v46, v47
	v_cvt_pk_bf16_f32 v35, v48, v49
	v_cvt_pk_bf16_f32 v36, v42, v43
	v_cvt_pk_bf16_f32 v37, v44, v45
	v_cvt_pk_bf16_f32 v38, v38, v39
	v_cvt_pk_bf16_f32 v39, v40, v41
	v_cvt_pk_bf16_f32 v40, v50, v51
	v_cvt_pk_bf16_f32 v41, v56, v57
	global_store_dwordx4 v[52:53], v[34:37], off
	global_store_dwordx4 v[52:53], v[38:41], off offset:256
;   DI void operator()(const f32x4 (&acc)[2][2][4][2], const pg8::Unit& u, int wr, int wc, int fr, int fq) const {
;     ...
;           f32x4 v0 = acc[ai][bj][m][0] * rs, v1 = acc[ai][bj][m][1] * rs;
;           if (MODE == EP_IN || MODE == EP_MIX || MODE == EP_DOWN) {
; #pragma unroll
;             for (int j = 0; j < 4; ++j) ssq += v0[j] * v0[j] + v1[j] * v1[j];
;           }
;           if (MODE == EP_UP) {
; #pragma unroll
;             for (int j = 0; j < 4; ++j) { float a = fmaxf(v0[j], 0.f), b = fmaxf(v1[j], 0.f); v0[j] = a * a; v1[j] = b * b; }
;           }
;           bf16_t* dst;
;           const int ct = bj * 128 + cl;
;           if (MODE == EP_IN) {
;             if (pn < 4) dst = (bf16_t*)(ws + OFF_PROJA) + (size_t)grow * 1024 + pn * 256 + ct;
;             else if (pn < 16) dst = (bf16_t*)(ws + OFF_PROJG) + (size_t)grow * 3072 + (pn - 4) * 256 + ct;
;             else dst = (bf16_t*)(ws + OFF_PROJS) + (size_t)grow * 256 + ct;
;           } else if (MODE == EP_Q) {
;             if (pn < 4) dst = (bf16_t*)(dout + DO_Q) + (size_t)grow * 1536 + (pn * 2 + bj) * 192 + cl;
;             else {
;               const int mm = (pn - 4) * 256 + ct, h = mm >> 6, r = mm & 63;
;               dst = (bf16_t*)(dout + DO_Q) + (size_t)grow * 1536 + h * 192 + 128 + r;
;               const int pos = grow < TP ? (grow & 4095) : grow - TP;
;               const f32x4* tb = (const f32x4*)((const f32x2*)(ws + OFF_ROPE) + pos * 32 + (r >> 1));
;               const f32x4 t0 = tb[0], t1 = tb[1];
;               f32x4 o0, o1;
;               o0[0] = v0[0] * t0[0] - v0[1] * t0[1]; o0[1] = v0[1] * t0[0] + v0[0] * t0[1];
;               o0[2] = v0[2] * t0[2] - v0[3] * t0[3]; o0[3] = v0[3] * t0[2] + v0[2] * t0[3];
;               o1[0] = v1[0] * t1[0] - v1[1] * t1[1]; o1[1] = v1[1] * t1[0] + v1[0] * t1[1];
;               o1[2] = v1[2] * t1[2] - v1[3] * t1[3]; o1[3] = v1[3] * t1[2] + v1[2] * t1[3];
;               v0 = o0; v1 = o1;
;             }
;           } else if (MODE == EP_KV) {
;             dst = (bf16_t*)(ws + OFF_XB) + (size_t)grow * 2048 + pn * 256 + ct;
;           } else if (MODE == EP_MIX) {
;             dst = (bf16_t*)(ws + OFF_MIX) + (size_t)grow * 2048 + pn * 256 + ct;
;           } else if (MODE == EP_UP) {
;             dst = (bf16_t*)(ws + OFF_U) + (size_t)row * 8192 + pn * 256 + ct;
;           } else {
	s_nop 0
	v_add_u32_e32 v36, 0xa0, v148
	v_ashrrev_i32_e32 v37, 31, v36
	v_lshlrev_b64 v[36:37], 14, v[36:37]
	v_lshl_add_u64 v[36:37], s[6:7], 0, v[36:37]
	v_add_u32_e32 v38, 0x40b0, v148
	v_lshl_add_u64 v[36:37], v[36:37], 0, s[18:19]
	v_ashrrev_i32_e32 v39, 31, v38
	v_lshl_add_u64 v[36:37], v[36:37], 0, v[138:139]
	v_lshl_add_u64 v[38:39], v[38:39], 2, s[4:5]
	v_mov_b32_e32 v34, v245
	v_pk_mul_f32 v[32:33], v[32:33], v[34:35] op_sel_hi:[1,0]
	v_pk_mul_f32 v[30:31], v[30:31], v[34:35] op_sel_hi:[1,0]
	v_pk_mul_f32 v[28:29], v[28:29], v[34:35] op_sel_hi:[1,0]
	v_pk_mul_f32 v[26:27], v[26:27], v[34:35] op_sel_hi:[1,0]
	v_pk_mul_f32 v[24:25], v[24:25], v[34:35] op_sel_hi:[1,0]
	v_pk_mul_f32 v[22:23], v[22:23], v[34:35] op_sel_hi:[1,0]
	v_pk_mul_f32 v[20:21], v[20:21], v[34:35] op_sel_hi:[1,0]
	v_pk_mul_f32 v[18:19], v[18:19], v[34:35] op_sel_hi:[1,0]
	v_max_f32_e32 v30, 0, v30
	v_max_f32_e32 v26, 0, v26
	v_max_f32_e32 v31, 0, v31
	v_max_f32_e32 v27, 0, v27
	v_max_f32_e32 v32, 0, v32
	v_max_f32_e32 v28, 0, v28
	v_max_f32_e32 v33, 0, v33
	v_max_f32_e32 v29, 0, v29
	v_max_f32_e32 v22, 0, v22
	v_max_f32_e32 v18, 0, v18
	v_max_f32_e32 v23, 0, v23
	v_max_f32_e32 v19, 0, v19
	v_max_f32_e32 v24, 0, v24
	v_max_f32_e32 v20, 0, v20
	v_max_f32_e32 v25, 0, v25
	v_max_f32_e32 v21, 0, v21
	v_pk_mul_f32 v[30:31], v[30:31], v[30:31]
	v_pk_mul_f32 v[26:27], v[26:27], v[26:27]
	v_pk_mul_f32 v[32:33], v[32:33], v[32:33]
	v_pk_mul_f32 v[28:29], v[28:29], v[28:29]
	v_pk_mul_f32 v[22:23], v[22:23], v[22:23]
	v_pk_mul_f32 v[34:35], v[18:19], v[18:19]
	v_pk_mul_f32 v[24:25], v[24:25], v[24:25]
	v_pk_mul_f32 v[40:41], v[20:21], v[20:21]
	v_cvt_pk_bf16_f32 v18, v30, v31
	v_cvt_pk_bf16_f32 v19, v32, v33
	v_cvt_pk_bf16_f32 v20, v26, v27
	v_cvt_pk_bf16_f32 v21, v28, v29
	v_cvt_pk_bf16_f32 v22, v22, v23
	v_cvt_pk_bf16_f32 v23, v24, v25
	v_cvt_pk_bf16_f32 v24, v34, v35
	v_cvt_pk_bf16_f32 v25, v40, v41
	global_store_dwordx4 v[36:37], v[18:21], off
	global_store_dwordx4 v[36:37], v[22:25], off offset:256
	s_nop 0
	v_add_u32_e32 v20, 0xb0, v148
	v_ashrrev_i32_e32 v21, 31, v20
	v_lshlrev_b64 v[20:21], 14, v[20:21]
	v_lshl_add_u64 v[20:21], s[6:7], 0, v[20:21]
	v_lshl_add_u64 v[20:21], v[20:21], 0, s[18:19]
	v_lshl_add_u64 v[20:21], v[20:21], 0, v[138:139]
	v_mov_b32_e32 v18, v246
	v_pk_mul_f32 v[16:17], v[16:17], v[18:19] op_sel_hi:[1,0]
	v_pk_mul_f32 v[14:15], v[14:15], v[18:19] op_sel_hi:[1,0]
	v_pk_mul_f32 v[12:13], v[12:13], v[18:19] op_sel_hi:[1,0]
	v_pk_mul_f32 v[10:11], v[10:11], v[18:19] op_sel_hi:[1,0]
	v_pk_mul_f32 v[8:9], v[8:9], v[18:19] op_sel_hi:[1,0]
	v_pk_mul_f32 v[6:7], v[6:7], v[18:19] op_sel_hi:[1,0]
	v_pk_mul_f32 v[4:5], v[4:5], v[18:19] op_sel_hi:[1,0]
	v_pk_mul_f32 v[2:3], v[2:3], v[18:19] op_sel_hi:[1,0]
	v_max_f32_e32 v14, 0, v14
	v_max_f32_e32 v10, 0, v10
	v_max_f32_e32 v15, 0, v15
	v_max_f32_e32 v11, 0, v11
	v_max_f32_e32 v16, 0, v16
	v_max_f32_e32 v12, 0, v12
	v_max_f32_e32 v17, 0, v17
	v_max_f32_e32 v13, 0, v13
	v_max_f32_e32 v6, 0, v6
	v_max_f32_e32 v2, 0, v2
	v_max_f32_e32 v7, 0, v7
	v_max_f32_e32 v3, 0, v3
	v_max_f32_e32 v8, 0, v8
	v_max_f32_e32 v4, 0, v4
	v_max_f32_e32 v9, 0, v9
	v_max_f32_e32 v5, 0, v5
	v_pk_mul_f32 v[14:15], v[14:15], v[14:15]
	v_pk_mul_f32 v[10:11], v[10:11], v[10:11]
	v_pk_mul_f32 v[16:17], v[16:17], v[16:17]
	v_pk_mul_f32 v[12:13], v[12:13], v[12:13]
	v_pk_mul_f32 v[6:7], v[6:7], v[6:7]
	v_pk_mul_f32 v[18:19], v[2:3], v[2:3]
	v_pk_mul_f32 v[8:9], v[8:9], v[8:9]
	v_pk_mul_f32 v[22:23], v[4:5], v[4:5]
	v_cvt_pk_bf16_f32 v2, v14, v15
	v_cvt_pk_bf16_f32 v3, v16, v17
	v_cvt_pk_bf16_f32 v4, v10, v11
	v_cvt_pk_bf16_f32 v5, v12, v13
	v_cvt_pk_bf16_f32 v6, v6, v7
	v_cvt_pk_bf16_f32 v7, v8, v9
	v_cvt_pk_bf16_f32 v8, v18, v19
	v_cvt_pk_bf16_f32 v9, v22, v23
	global_store_dwordx4 v[20:21], v[2:5], off
	global_store_dwordx4 v[20:21], v[6:9], off offset:256
	s_cbranch_vccz .LBB0_1008
	s_waitcnt vmcnt(0)
	s_cmpk_gt_u32 s24, 0xff
	s_cbranch_scc1 .LBB0_1019
	s_barrier
